# hand-written lean residual epilogue (hoisted xb loads, packed square-sum, batched cross-lane reductions) for FFN-down and mixer-out GEMMs
# speedup vs baseline: 1.0060x; 1.0028x over previous
; #define PG8_STAGE(bufoff, gbase, voff) do { _Pragma("unroll") for (int _i = 0; _i < 2; ++_i) \
;         __builtin_amdgcn_global_load_lds((const unsigned*)((const char*)(gbase) + (voff)[_i]), (LAS unsigned*)(lds + (bufoff) + ldsw + _i * 8192), 16, 0, 0); } while (0)
; #define PG8_LDA(dst, b, h) do { _Pragma("unroll") for (int m = 0; m < 4; ++m) _Pragma("unroll") for (int k = 0; k < 2; ++k) dst[m][k] = *(const LAS bf16x8*)(lds + PG8_SA(b, h) + aoff + m * 2048 + k * 1024); } while (0)
; #define PG8_LDB(dst, b, h) do { _Pragma("unroll") for (int n = 0; n < 2; ++n) _Pragma("unroll") for (int k = 0; k < 2; ++k) dst[n][k] = *(const LAS bf16x8*)(lds + PG8_SB(b, h) + boff + n * 2048 + k * 1024); } while (0)
; #define PG8_MMA(ai, bj, At, Bt) do { __builtin_amdgcn_s_setprio(1); _Pragma("unroll") for (int m = 0; m < 4; ++m) _Pragma("unroll") for (int n = 0; n < 2; ++n) _Pragma("unroll") for (int k = 0; k < 2; ++k) \
;         acc[ai][bj][m][n] = __builtin_amdgcn_mfma_f32_16x16x32_bf16(Bt[n][k], At[m][k], acc[ai][bj][m][n], 0, 0, 0); __builtin_amdgcn_s_setprio(0); } while (0)
; #define PG8_WAIT_V(n) asm volatile("s_waitcnt vmcnt(" #n ")" ::: "memory")
; #define PG8_WAIT_L(n) asm volatile("s_waitcnt lgkmcnt(" #n ")" ::: "memory")
; #define PG8_BAR __builtin_amdgcn_s_barrier()
; #define PG8_SCHED __builtin_amdgcn_sched_barrier(0)
; template <class Epi, bool ALIGN_EPI>
; __device__ __forceinline__ void gemm_phase(LAS unsigned char* lds, const Gemm g, const StaticOrder& S, const Epi& E, const int tid) {
;     ...
;         const char* nA = has_next ? (const char*)g.A + (size_t)nxt.pm * tstepA + (size_t)nxt.pn * g.acs : cA; const char* nB = has_next ? (const char*)g.Bt + (size_t)nxt.pn * tstepB : cB;
;         for (int t = 0; t < nt; t += 2) {
;             const bool last = (t == nt - 2);
;             const char* a1 = cA + (size_t)(t + 1) * kstepA;
;             const char* a2 = last ? nA : cA + (size_t)(t + 2) * kstepA; const char* b2 = last ? nB : cB + (size_t)(t + 2) * kstepB;
;             const char* a3 = a2 + kstepA; const char* b3 = b2 + kstepB;
;             PG8_LDB(B0, 0, 0); PG8_LDB(B1, 0, 1); PG8_SCHED; PG8_LDA(At, 0, 0); PG8_STAGE(PG8_SA(1, 1), a1 + hstepA, voffA);
;             PG8_WAIT_V(8); PG8_WAIT_L(0); PG8_BAR; PG8_MMA(0, 0, At, B0); PG8_MMA(0, 1, At, B1); PG8_BAR; PG8_SCHED;
.LBB0_294:
	s_add_u32 s22, s10, 0x4000
	s_addc_u32 s23, s11, 0
	s_cmpk_eq_i32 s86, 0x54
	s_cselect_b32 s42, s48, s22
	s_cselect_b32 s43, s49, s23
	s_cselect_b32 s34, s50, s84
	s_cselect_b32 s35, s51, s85
	s_add_u32 s22, s42, 0x8000
	s_addc_u32 s23, s43, 0
	s_add_i32 s87, 0, 0x10000
	v_add_u32_e32 v0, s87, v154
	s_add_i32 s90, 0, 0x14000
	s_waitcnt lgkmcnt(0)
	ds_read_b128 v[132:135], v0
	ds_read_b128 v[148:151], v0 offset:1024
	ds_read_b128 v[156:159], v0 offset:2048
	ds_read_b128 v[160:163], v0 offset:3072
	v_add_u32_e32 v0, s90, v154
	ds_read_b128 v[164:167], v0
	ds_read_b128 v[168:171], v0 offset:1024
	ds_read_b128 v[172:175], v0 offset:2048
	ds_read_b128 v[176:179], v0 offset:3072
	s_add_i32 m0, s57, 0xc000
	ds_read_b128 v[180:183], v155
	ds_read_b128 v[184:187], v155 offset:1024
	ds_read_b128 v[188:191], v155 offset:2048
	ds_read_b128 v[192:195], v155 offset:3072
	ds_read_b128 v[196:199], v155 offset:4096
	ds_read_b128 v[214:217], v155 offset:5120
	ds_read_b128 v[218:221], v155 offset:6144

; #define PG8_STAGE(bufoff, gbase, voff) do { _Pragma("unroll") for (int _i = 0; _i < 2; ++_i) \
;         __builtin_amdgcn_global_load_lds((const unsigned*)((const char*)(gbase) + (voff)[_i]), (LAS unsigned*)(lds + (bufoff) + ldsw + _i * 8192), 16, 0, 0); } while (0)
; #define PG8_LDA(dst, b, h) do { _Pragma("unroll") for (int m = 0; m < 4; ++m) _Pragma("unroll") for (int k = 0; k < 2; ++k) dst[m][k] = *(const LAS bf16x8*)(lds + PG8_SA(b, h) + aoff + m * 2048 + k * 1024); } while (0)
; #define PG8_LDB(dst, b, h) do { _Pragma("unroll") for (int n = 0; n < 2; ++n) _Pragma("unroll") for (int k = 0; k < 2; ++k) dst[n][k] = *(const LAS bf16x8*)(lds + PG8_SB(b, h) + boff + n * 2048 + k * 1024); } while (0)
; #define PG8_MMA(ai, bj, At, Bt) do { __builtin_amdgcn_s_setprio(1); _Pragma("unroll") for (int m = 0; m < 4; ++m) _Pragma("unroll") for (int n = 0; n < 2; ++n) _Pragma("unroll") for (int k = 0; k < 2; ++k) \
;         acc[ai][bj][m][n] = __builtin_amdgcn_mfma_f32_16x16x32_bf16(Bt[n][k], At[m][k], acc[ai][bj][m][n], 0, 0, 0); __builtin_amdgcn_s_setprio(0); } while (0)
; #define PG8_WAIT_V(n) asm volatile("s_waitcnt vmcnt(" #n ")" ::: "memory")
; #define PG8_WAIT_L(n) asm volatile("s_waitcnt lgkmcnt(" #n ")" ::: "memory")
; #define PG8_BAR __builtin_amdgcn_s_barrier()
; #define PG8_SCHED __builtin_amdgcn_sched_barrier(0)
; template <class Epi, bool ALIGN_EPI>
; __device__ __forceinline__ void gemm_phase(LAS unsigned char* lds, const Gemm g, const StaticOrder& S, const Epi& E, const int tid) {
;     ...
;             PG8_LDB(B0, 0, 0); PG8_LDB(B1, 0, 1); PG8_SCHED; PG8_LDA(At, 0, 0); PG8_STAGE(PG8_SA(1, 1), a1 + hstepA, voffA);
;             PG8_WAIT_V(8); PG8_WAIT_L(0); PG8_BAR; PG8_MMA(0, 0, At, B0); PG8_MMA(0, 1, At, B1); PG8_BAR; PG8_SCHED;
	global_load_lds_dwordx4 v144, s[10:11]
	s_add_i32 m0, s57, 0xe000
	ds_read_b128 v[222:225], v155 offset:7168
	global_load_lds_dwordx4 v146, s[10:11]
	s_waitcnt vmcnt(8)
	s_waitcnt lgkmcnt(0)
	s_barrier


; #define PG8_MMA(ai, bj, At, Bt) do { __builtin_amdgcn_s_setprio(1); _Pragma("unroll") for (int m = 0; m < 4; ++m) _Pragma("unroll") for (int n = 0; n < 2; ++n) _Pragma("unroll") for (int k = 0; k < 2; ++k) \
;         acc[ai][bj][m][n] = __builtin_amdgcn_mfma_f32_16x16x32_bf16(Bt[n][k], At[m][k], acc[ai][bj][m][n], 0, 0, 0); __builtin_amdgcn_s_setprio(0); } while (0)
; #define PG8_WAIT_V(n) asm volatile("s_waitcnt vmcnt(" #n ")" ::: "memory")
; #define PG8_WAIT_L(n) asm volatile("s_waitcnt lgkmcnt(" #n ")" ::: "memory")
; #define PG8_BAR __builtin_amdgcn_s_barrier()
; #define PG8_SCHED __builtin_amdgcn_sched_barrier(0)
; template <class Epi, bool ALIGN_EPI>
; __device__ __forceinline__ void gemm_phase(LAS unsigned char* lds, const Gemm g, const StaticOrder& S, const Epi& E, const int tid) {
;     ...
;             PG8_WAIT_V(8); PG8_WAIT_L(0); PG8_BAR; PG8_MMA(0, 0, At, B0); PG8_MMA(0, 1, At, B1); PG8_BAR; PG8_SCHED;
	v_mfma_f32_16x16x32_bf16 v[8:11], v[132:135], v[180:183], v[8:11]
	v_mfma_f32_16x16x32_bf16 v[56:59], v[156:159], v[180:183], v[56:59]
	v_mfma_f32_16x16x32_bf16 v[52:55], v[132:135], v[188:191], v[52:55]
	v_mfma_f32_16x16x32_bf16 v[48:51], v[156:159], v[188:191], v[48:51]
	v_mfma_f32_16x16x32_bf16 v[44:47], v[132:135], v[196:199], v[44:47]
	v_mfma_f32_16x16x32_bf16 v[40:43], v[156:159], v[196:199], v[40:43]
	v_mfma_f32_16x16x32_bf16 v[36:39], v[132:135], v[218:221], v[36:39]
	v_mfma_f32_16x16x32_bf16 v[32:35], v[156:159], v[218:221], v[32:35]
	v_mfma_f32_16x16x32_bf16 v[8:11], v[148:151], v[184:187], v[8:11]
	v_mfma_f32_16x16x32_bf16 v[56:59], v[160:163], v[184:187], v[56:59]
	v_mfma_f32_16x16x32_bf16 v[52:55], v[148:151], v[192:195], v[52:55]
	v_mfma_f32_16x16x32_bf16 v[48:51], v[160:163], v[192:195], v[48:51]
	v_mfma_f32_16x16x32_bf16 v[44:47], v[148:151], v[214:217], v[44:47]
	v_mfma_f32_16x16x32_bf16 v[40:43], v[160:163], v[214:217], v[40:43]
	v_mfma_f32_16x16x32_bf16 v[36:39], v[148:151], v[222:225], v[36:39]
	v_mfma_f32_16x16x32_bf16 v[32:35], v[160:163], v[222:225], v[32:35]


; #define PG8_MMA(ai, bj, At, Bt) do { __builtin_amdgcn_s_setprio(1); _Pragma("unroll") for (int m = 0; m < 4; ++m) _Pragma("unroll") for (int n = 0; n < 2; ++n) _Pragma("unroll") for (int k = 0; k < 2; ++k) \
;         acc[ai][bj][m][n] = __builtin_amdgcn_mfma_f32_16x16x32_bf16(Bt[n][k], At[m][k], acc[ai][bj][m][n], 0, 0, 0); __builtin_amdgcn_s_setprio(0); } while (0)
; #define PG8_WAIT_V(n) asm volatile("s_waitcnt vmcnt(" #n ")" ::: "memory")
; #define PG8_WAIT_L(n) asm volatile("s_waitcnt lgkmcnt(" #n ")" ::: "memory")
; #define PG8_BAR __builtin_amdgcn_s_barrier()
; #define PG8_SCHED __builtin_amdgcn_sched_barrier(0)
; template <class Epi, bool ALIGN_EPI>
; __device__ __forceinline__ void gemm_phase(LAS unsigned char* lds, const Gemm g, const StaticOrder& S, const Epi& E, const int tid) {
;     ...
;             PG8_WAIT_V(8); PG8_WAIT_L(0); PG8_BAR; PG8_MMA(0, 0, At, B0); PG8_MMA(0, 1, At, B1); PG8_BAR; PG8_SCHED;
	v_mfma_f32_16x16x32_bf16 v[2:5], v[164:167], v[180:183], v[4:7]
	v_mfma_f32_16x16x32_bf16 v[28:31], v[172:175], v[180:183], v[28:31]
	v_mfma_f32_16x16x32_bf16 v[96:99], v[164:167], v[188:191], v[96:99]
	v_mfma_f32_16x16x32_bf16 v[92:95], v[172:175], v[188:191], v[92:95]
	v_mfma_f32_16x16x32_bf16 v[88:91], v[164:167], v[196:199], v[88:91]
	v_mfma_f32_16x16x32_bf16 v[84:87], v[172:175], v[196:199], v[84:87]
	v_mfma_f32_16x16x32_bf16 v[80:83], v[164:167], v[218:221], v[80:83]
	v_mfma_f32_16x16x32_bf16 v[76:79], v[172:175], v[218:221], v[76:79]
	v_mfma_f32_16x16x32_bf16 v[2:5], v[168:171], v[184:187], v[2:5]
	v_mfma_f32_16x16x32_bf16 v[28:31], v[176:179], v[184:187], v[28:31]
	v_mfma_f32_16x16x32_bf16 v[96:99], v[168:171], v[192:195], v[96:99]
	v_mfma_f32_16x16x32_bf16 v[92:95], v[176:179], v[192:195], v[92:95]
	v_mfma_f32_16x16x32_bf16 v[88:91], v[168:171], v[214:217], v[88:91]
	v_mfma_f32_16x16x32_bf16 v[84:87], v[176:179], v[214:217], v[84:87]
	v_mfma_f32_16x16x32_bf16 v[80:83], v[168:171], v[222:225], v[80:83]
	v_mfma_f32_16x16x32_bf16 v[76:79], v[176:179], v[222:225], v[76:79]

; #define PG8_STAGE(bufoff, gbase, voff) do { _Pragma("unroll") for (int _i = 0; _i < 2; ++_i) \
;         __builtin_amdgcn_global_load_lds((const unsigned*)((const char*)(gbase) + (voff)[_i]), (LAS unsigned*)(lds + (bufoff) + ldsw + _i * 8192), 16, 0, 0); } while (0)
; #define PG8_LDA(dst, b, h) do { _Pragma("unroll") for (int m = 0; m < 4; ++m) _Pragma("unroll") for (int k = 0; k < 2; ++k) dst[m][k] = *(const LAS bf16x8*)(lds + PG8_SA(b, h) + aoff + m * 2048 + k * 1024); } while (0)
; template <class Epi, bool ALIGN_EPI>
; __device__ __forceinline__ void gemm_phase(LAS unsigned char* lds, const Gemm g, const StaticOrder& S, const Epi& E, const int tid) {
;     ...
;             PG8_LDA(At, 0, 1); PG8_STAGE(PG8_SB(0, 0), b2, voffB); PG8_STAGE(PG8_SB(0, 1), b2 + hstepB, voffB); PG8_STAGE(PG8_SA(0, 0), a2, voffA);
	s_barrier
	s_add_i32 s87, s87, s56
	s_mov_b32 m0, s87
	ds_read_b128 v[180:183], v155 offset:16384
	ds_read_b128 v[184:187], v155 offset:17408
	ds_read_b128 v[188:191], v155 offset:18432
	ds_read_b128 v[192:195], v155 offset:19456


; #define PG8_STAGE(bufoff, gbase, voff) do { _Pragma("unroll") for (int _i = 0; _i < 2; ++_i) \
;         __builtin_amdgcn_global_load_lds((const unsigned*)((const char*)(gbase) + (voff)[_i]), (LAS unsigned*)(lds + (bufoff) + ldsw + _i * 8192), 16, 0, 0); } while (0)
; #define PG8_LDA(dst, b, h) do { _Pragma("unroll") for (int m = 0; m < 4; ++m) _Pragma("unroll") for (int k = 0; k < 2; ++k) dst[m][k] = *(const LAS bf16x8*)(lds + PG8_SA(b, h) + aoff + m * 2048 + k * 1024); } while (0)
; #define PG8_MMA(ai, bj, At, Bt) do { __builtin_amdgcn_s_setprio(1); _Pragma("unroll") for (int m = 0; m < 4; ++m) _Pragma("unroll") for (int n = 0; n < 2; ++n) _Pragma("unroll") for (int k = 0; k < 2; ++k) \
;         acc[ai][bj][m][n] = __builtin_amdgcn_mfma_f32_16x16x32_bf16(Bt[n][k], At[m][k], acc[ai][bj][m][n], 0, 0, 0); __builtin_amdgcn_s_setprio(0); } while (0)
; #define PG8_WAIT_V(n) asm volatile("s_waitcnt vmcnt(" #n ")" ::: "memory")
; #define PG8_WAIT_L(n) asm volatile("s_waitcnt lgkmcnt(" #n ")" ::: "memory")
; #define PG8_BAR __builtin_amdgcn_s_barrier()
; #define PG8_SCHED __builtin_amdgcn_sched_barrier(0)
; template <class Epi, bool ALIGN_EPI>
; __device__ __forceinline__ void gemm_phase(LAS unsigned char* lds, const Gemm g, const StaticOrder& S, const Epi& E, const int tid) {
;     ...
;             PG8_LDA(At, 0, 1); PG8_STAGE(PG8_SB(0, 0), b2, voffB); PG8_STAGE(PG8_SB(0, 1), b2 + hstepB, voffB); PG8_STAGE(PG8_SA(0, 0), a2, voffA);
;             PG8_WAIT_V(8); PG8_WAIT_L(0); PG8_BAR; PG8_MMA(1, 0, At, B0); PG8_MMA(1, 1, At, B1); PG8_BAR; PG8_SCHED;
	global_load_lds_dwordx4 v140, s[34:35]
	s_add_i32 m0, s87, 0x2000
	s_add_u32 s88, s34, 0x4000
	s_addc_u32 s89, s35, 0
	s_add_i32 s87, s90, s56
	global_load_lds_dwordx4 v136, s[34:35]
	s_mov_b32 m0, s87
	ds_read_b128 v[222:225], v155 offset:23552
	global_load_lds_dwordx4 v140, s[88:89]
	s_add_i32 m0, s87, 0x2000
	ds_read_b128 v[218:221], v155 offset:22528
	global_load_lds_dwordx4 v136, s[88:89]
	s_mov_b32 m0, s57
	ds_read_b128 v[214:217], v155 offset:21504
	global_load_lds_dwordx4 v142, s[42:43]
	s_mov_b32 m0, s60
	ds_read_b128 v[196:199], v155 offset:20480
	global_load_lds_dwordx4 v138, s[42:43]
	s_waitcnt vmcnt(8)
	s_waitcnt lgkmcnt(0)
	s_barrier


; #define PG8_MMA(ai, bj, At, Bt) do { __builtin_amdgcn_s_setprio(1); _Pragma("unroll") for (int m = 0; m < 4; ++m) _Pragma("unroll") for (int n = 0; n < 2; ++n) _Pragma("unroll") for (int k = 0; k < 2; ++k) \
;         acc[ai][bj][m][n] = __builtin_amdgcn_mfma_f32_16x16x32_bf16(Bt[n][k], At[m][k], acc[ai][bj][m][n], 0, 0, 0); __builtin_amdgcn_s_setprio(0); } while (0)
; #define PG8_WAIT_V(n) asm volatile("s_waitcnt vmcnt(" #n ")" ::: "memory")
; #define PG8_WAIT_L(n) asm volatile("s_waitcnt lgkmcnt(" #n ")" ::: "memory")
; #define PG8_BAR __builtin_amdgcn_s_barrier()
; #define PG8_SCHED __builtin_amdgcn_sched_barrier(0)
; template <class Epi, bool ALIGN_EPI>
; __device__ __forceinline__ void gemm_phase(LAS unsigned char* lds, const Gemm g, const StaticOrder& S, const Epi& E, const int tid) {
;     ...
;             PG8_WAIT_V(8); PG8_WAIT_L(0); PG8_BAR; PG8_MMA(1, 0, At, B0); PG8_MMA(1, 1, At, B1); PG8_BAR; PG8_SCHED;
	v_mfma_f32_16x16x32_bf16 v[24:27], v[132:135], v[180:183], v[24:27]
	v_mfma_f32_16x16x32_bf16 v[20:23], v[156:159], v[180:183], v[20:23]
	v_mfma_f32_16x16x32_bf16 v[64:67], v[132:135], v[188:191], v[64:67]
	v_mfma_f32_16x16x32_bf16 v[72:75], v[156:159], v[188:191], v[72:75]
	v_mfma_f32_16x16x32_bf16 v[16:19], v[132:135], v[196:199], v[16:19]
	v_mfma_f32_16x16x32_bf16 v[12:15], v[156:159], v[196:199], v[12:15]
	v_mfma_f32_16x16x32_bf16 v[60:63], v[132:135], v[218:221], v[60:63]
	v_mfma_f32_16x16x32_bf16 v[68:71], v[156:159], v[218:221], v[68:71]
	v_mfma_f32_16x16x32_bf16 v[24:27], v[148:151], v[184:187], v[24:27]
	v_mfma_f32_16x16x32_bf16 v[20:23], v[160:163], v[184:187], v[20:23]
	v_mfma_f32_16x16x32_bf16 v[64:67], v[148:151], v[192:195], v[64:67]
	v_mfma_f32_16x16x32_bf16 v[72:75], v[160:163], v[192:195], v[72:75]
	v_mfma_f32_16x16x32_bf16 v[16:19], v[148:151], v[214:217], v[16:19]
	v_mfma_f32_16x16x32_bf16 v[12:15], v[160:163], v[214:217], v[12:15]
	v_mfma_f32_16x16x32_bf16 v[60:63], v[148:151], v[222:225], v[60:63]
	v_mfma_f32_16x16x32_bf16 v[68:71], v[160:163], v[222:225], v[68:71]


; #define PG8_MMA(ai, bj, At, Bt) do { __builtin_amdgcn_s_setprio(1); _Pragma("unroll") for (int m = 0; m < 4; ++m) _Pragma("unroll") for (int n = 0; n < 2; ++n) _Pragma("unroll") for (int k = 0; k < 2; ++k) \
;         acc[ai][bj][m][n] = __builtin_amdgcn_mfma_f32_16x16x32_bf16(Bt[n][k], At[m][k], acc[ai][bj][m][n], 0, 0, 0); __builtin_amdgcn_s_setprio(0); } while (0)
; #define PG8_WAIT_V(n) asm volatile("s_waitcnt vmcnt(" #n ")" ::: "memory")
; #define PG8_WAIT_L(n) asm volatile("s_waitcnt lgkmcnt(" #n ")" ::: "memory")
; #define PG8_BAR __builtin_amdgcn_s_barrier()
; #define PG8_SCHED __builtin_amdgcn_sched_barrier(0)
; template <class Epi, bool ALIGN_EPI>
; __device__ __forceinline__ void gemm_phase(LAS unsigned char* lds, const Gemm g, const StaticOrder& S, const Epi& E, const int tid) {
;     ...
;             PG8_WAIT_V(8); PG8_WAIT_L(0); PG8_BAR; PG8_MMA(1, 0, At, B0); PG8_MMA(1, 1, At, B1); PG8_BAR; PG8_SCHED;
	v_mfma_f32_16x16x32_bf16 v[128:131], v[164:167], v[180:183], v[128:131]
	v_mfma_f32_16x16x32_bf16 v[124:127], v[172:175], v[180:183], v[124:127]
	v_mfma_f32_16x16x32_bf16 v[120:123], v[164:167], v[188:191], v[120:123]
	v_mfma_f32_16x16x32_bf16 v[116:119], v[172:175], v[188:191], v[116:119]
	v_mfma_f32_16x16x32_bf16 v[112:115], v[164:167], v[196:199], v[112:115]
	v_mfma_f32_16x16x32_bf16 v[108:111], v[172:175], v[196:199], v[108:111]
	v_mfma_f32_16x16x32_bf16 v[104:107], v[164:167], v[218:221], v[104:107]
	v_mfma_f32_16x16x32_bf16 v[100:103], v[172:175], v[218:221], v[100:103]
	v_mfma_f32_16x16x32_bf16 v[128:131], v[168:171], v[184:187], v[128:131]
	v_mfma_f32_16x16x32_bf16 v[124:127], v[176:179], v[184:187], v[124:127]
	v_mfma_f32_16x16x32_bf16 v[120:123], v[168:171], v[192:195], v[120:123]
	v_mfma_f32_16x16x32_bf16 v[116:119], v[176:179], v[192:195], v[116:119]
	v_mfma_f32_16x16x32_bf16 v[112:115], v[168:171], v[214:217], v[112:115]
	v_mfma_f32_16x16x32_bf16 v[108:111], v[176:179], v[214:217], v[108:111]
	v_mfma_f32_16x16x32_bf16 v[104:107], v[168:171], v[222:225], v[104:107]
	v_mfma_f32_16x16x32_bf16 v[100:103], v[176:179], v[222:225], v[100:103]

; #define PG8_STAGE(bufoff, gbase, voff) do { _Pragma("unroll") for (int _i = 0; _i < 2; ++_i) \
;         __builtin_amdgcn_global_load_lds((const unsigned*)((const char*)(gbase) + (voff)[_i]), (LAS unsigned*)(lds + (bufoff) + ldsw + _i * 8192), 16, 0, 0); } while (0)
; #define PG8_LDA(dst, b, h) do { _Pragma("unroll") for (int m = 0; m < 4; ++m) _Pragma("unroll") for (int k = 0; k < 2; ++k) dst[m][k] = *(const LAS bf16x8*)(lds + PG8_SA(b, h) + aoff + m * 2048 + k * 1024); } while (0)
; #define PG8_LDB(dst, b, h) do { _Pragma("unroll") for (int n = 0; n < 2; ++n) _Pragma("unroll") for (int k = 0; k < 2; ++k) dst[n][k] = *(const LAS bf16x8*)(lds + PG8_SB(b, h) + boff + n * 2048 + k * 1024); } while (0)
; #define PG8_SCHED __builtin_amdgcn_sched_barrier(0)
; template <class Epi, bool ALIGN_EPI>
; __device__ __forceinline__ void gemm_phase(LAS unsigned char* lds, const Gemm g, const StaticOrder& S, const Epi& E, const int tid) {
;     ...
;             PG8_LDB(B0, 1, 0); PG8_LDB(B1, 1, 1); PG8_SCHED; PG8_LDA(At, 1, 0); PG8_STAGE(PG8_SA(0, 1), a2 + hstepA, voffA);
	s_barrier
	s_add_i32 s87, 0, 0x18000
	v_add_u32_e32 v0, s87, v154
	s_add_i32 s88, 0, 0x1c000
	ds_read_b128 v[132:135], v0
	ds_read_b128 v[148:151], v0 offset:1024
	ds_read_b128 v[156:159], v0 offset:2048
	ds_read_b128 v[160:163], v0 offset:3072
	v_add_u32_e32 v0, s88, v154
	ds_read_b128 v[164:167], v0
	ds_read_b128 v[168:171], v0 offset:1024
	ds_read_b128 v[172:175], v0 offset:2048
	ds_read_b128 v[176:179], v0 offset:3072
	s_add_u32 s42, s42, 0x4000
	s_addc_u32 s43, s43, 0
	s_mov_b32 m0, s61
	ds_read_b128 v[180:183], v155 offset:32768
	ds_read_b128 v[184:187], v155 offset:33792
	ds_read_b128 v[188:191], v155 offset:34816
	ds_read_b128 v[192:195], v155 offset:35840
	ds_read_b128 v[196:199], v155 offset:36864
	ds_read_b128 v[214:217], v155 offset:37888
	ds_read_b128 v[218:221], v155 offset:38912

; #define PG8_STAGE(bufoff, gbase, voff) do { _Pragma("unroll") for (int _i = 0; _i < 2; ++_i) \
;         __builtin_amdgcn_global_load_lds((const unsigned*)((const char*)(gbase) + (voff)[_i]), (LAS unsigned*)(lds + (bufoff) + ldsw + _i * 8192), 16, 0, 0); } while (0)
; #define PG8_LDA(dst, b, h) do { _Pragma("unroll") for (int m = 0; m < 4; ++m) _Pragma("unroll") for (int k = 0; k < 2; ++k) dst[m][k] = *(const LAS bf16x8*)(lds + PG8_SA(b, h) + aoff + m * 2048 + k * 1024); } while (0)
; #define PG8_LDB(dst, b, h) do { _Pragma("unroll") for (int n = 0; n < 2; ++n) _Pragma("unroll") for (int k = 0; k < 2; ++k) dst[n][k] = *(const LAS bf16x8*)(lds + PG8_SB(b, h) + boff + n * 2048 + k * 1024); } while (0)
; #define PG8_MMA(ai, bj, At, Bt) do { __builtin_amdgcn_s_setprio(1); _Pragma("unroll") for (int m = 0; m < 4; ++m) _Pragma("unroll") for (int n = 0; n < 2; ++n) _Pragma("unroll") for (int k = 0; k < 2; ++k) \
;         acc[ai][bj][m][n] = __builtin_amdgcn_mfma_f32_16x16x32_bf16(Bt[n][k], At[m][k], acc[ai][bj][m][n], 0, 0, 0); __builtin_amdgcn_s_setprio(0); } while (0)
; #define PG8_WAIT_V(n) asm volatile("s_waitcnt vmcnt(" #n ")" ::: "memory")
; #define PG8_WAIT_L(n) asm volatile("s_waitcnt lgkmcnt(" #n ")" ::: "memory")
; #define PG8_BAR __builtin_amdgcn_s_barrier()
; #define PG8_SCHED __builtin_amdgcn_sched_barrier(0)
; template <class Epi, bool ALIGN_EPI>
; __device__ __forceinline__ void gemm_phase(LAS unsigned char* lds, const Gemm g, const StaticOrder& S, const Epi& E, const int tid) {
;     ...
;             PG8_LDB(B0, 1, 0); PG8_LDB(B1, 1, 1); PG8_SCHED; PG8_LDA(At, 1, 0); PG8_STAGE(PG8_SA(0, 1), a2 + hstepA, voffA);
;             PG8_WAIT_V(8); PG8_WAIT_L(0); PG8_BAR; PG8_MMA(0, 0, At, B0); PG8_MMA(0, 1, At, B1); PG8_BAR; PG8_SCHED;
	global_load_lds_dwordx4 v142, s[42:43]
	s_mov_b32 m0, s71
	ds_read_b128 v[222:225], v155 offset:39936
	global_load_lds_dwordx4 v138, s[42:43]
	s_waitcnt vmcnt(8)
	s_waitcnt lgkmcnt(0)
	s_barrier


; #define PG8_MMA(ai, bj, At, Bt) do { __builtin_amdgcn_s_setprio(1); _Pragma("unroll") for (int m = 0; m < 4; ++m) _Pragma("unroll") for (int n = 0; n < 2; ++n) _Pragma("unroll") for (int k = 0; k < 2; ++k) \
;         acc[ai][bj][m][n] = __builtin_amdgcn_mfma_f32_16x16x32_bf16(Bt[n][k], At[m][k], acc[ai][bj][m][n], 0, 0, 0); __builtin_amdgcn_s_setprio(0); } while (0)
; #define PG8_WAIT_V(n) asm volatile("s_waitcnt vmcnt(" #n ")" ::: "memory")
; #define PG8_WAIT_L(n) asm volatile("s_waitcnt lgkmcnt(" #n ")" ::: "memory")
; #define PG8_BAR __builtin_amdgcn_s_barrier()
; #define PG8_SCHED __builtin_amdgcn_sched_barrier(0)
; template <class Epi, bool ALIGN_EPI>
; __device__ __forceinline__ void gemm_phase(LAS unsigned char* lds, const Gemm g, const StaticOrder& S, const Epi& E, const int tid) {
;     ...
;             PG8_WAIT_V(8); PG8_WAIT_L(0); PG8_BAR; PG8_MMA(0, 0, At, B0); PG8_MMA(0, 1, At, B1); PG8_BAR; PG8_SCHED;
	v_mfma_f32_16x16x32_bf16 v[6:9], v[132:135], v[180:183], v[8:11]
	v_mfma_f32_16x16x32_bf16 v[56:59], v[156:159], v[180:183], v[56:59]
	v_mfma_f32_16x16x32_bf16 v[52:55], v[132:135], v[188:191], v[52:55]
	v_mfma_f32_16x16x32_bf16 v[48:51], v[156:159], v[188:191], v[48:51]
	v_mfma_f32_16x16x32_bf16 v[44:47], v[132:135], v[196:199], v[44:47]
	v_mfma_f32_16x16x32_bf16 v[40:43], v[156:159], v[196:199], v[40:43]
	v_mfma_f32_16x16x32_bf16 v[36:39], v[132:135], v[218:221], v[36:39]
	v_mfma_f32_16x16x32_bf16 v[32:35], v[156:159], v[218:221], v[32:35]
	v_mfma_f32_16x16x32_bf16 v[8:11], v[148:151], v[184:187], v[6:9]
	v_mfma_f32_16x16x32_bf16 v[56:59], v[160:163], v[184:187], v[56:59]
	v_mfma_f32_16x16x32_bf16 v[52:55], v[148:151], v[192:195], v[52:55]
	v_mfma_f32_16x16x32_bf16 v[48:51], v[160:163], v[192:195], v[48:51]
	v_mfma_f32_16x16x32_bf16 v[44:47], v[148:151], v[214:217], v[44:47]
	v_mfma_f32_16x16x32_bf16 v[40:43], v[160:163], v[214:217], v[40:43]
	v_mfma_f32_16x16x32_bf16 v[36:39], v[148:151], v[222:225], v[36:39]
	v_mfma_f32_16x16x32_bf16 v[32:35], v[160:163], v[222:225], v[32:35]


; #define PG8_MMA(ai, bj, At, Bt) do { __builtin_amdgcn_s_setprio(1); _Pragma("unroll") for (int m = 0; m < 4; ++m) _Pragma("unroll") for (int n = 0; n < 2; ++n) _Pragma("unroll") for (int k = 0; k < 2; ++k) \
;         acc[ai][bj][m][n] = __builtin_amdgcn_mfma_f32_16x16x32_bf16(Bt[n][k], At[m][k], acc[ai][bj][m][n], 0, 0, 0); __builtin_amdgcn_s_setprio(0); } while (0)
; #define PG8_WAIT_V(n) asm volatile("s_waitcnt vmcnt(" #n ")" ::: "memory")
; #define PG8_WAIT_L(n) asm volatile("s_waitcnt lgkmcnt(" #n ")" ::: "memory")
; #define PG8_BAR __builtin_amdgcn_s_barrier()
; #define PG8_SCHED __builtin_amdgcn_sched_barrier(0)
; template <class Epi, bool ALIGN_EPI>
; __device__ __forceinline__ void gemm_phase(LAS unsigned char* lds, const Gemm g, const StaticOrder& S, const Epi& E, const int tid) {
;     ...
;             PG8_WAIT_V(8); PG8_WAIT_L(0); PG8_BAR; PG8_MMA(0, 0, At, B0); PG8_MMA(0, 1, At, B1); PG8_BAR; PG8_SCHED;
	v_mfma_f32_16x16x32_bf16 v[2:5], v[164:167], v[180:183], v[2:5]
	v_mfma_f32_16x16x32_bf16 v[28:31], v[172:175], v[180:183], v[28:31]
	v_mfma_f32_16x16x32_bf16 v[96:99], v[164:167], v[188:191], v[96:99]
	v_mfma_f32_16x16x32_bf16 v[92:95], v[172:175], v[188:191], v[92:95]
	v_mfma_f32_16x16x32_bf16 v[88:91], v[164:167], v[196:199], v[88:91]
	v_mfma_f32_16x16x32_bf16 v[84:87], v[172:175], v[196:199], v[84:87]
	v_mfma_f32_16x16x32_bf16 v[80:83], v[164:167], v[218:221], v[80:83]
	v_mfma_f32_16x16x32_bf16 v[76:79], v[172:175], v[218:221], v[76:79]
	v_mfma_f32_16x16x32_bf16 v[4:7], v[168:171], v[184:187], v[2:5]
	v_mfma_f32_16x16x32_bf16 v[28:31], v[176:179], v[184:187], v[28:31]
	v_mfma_f32_16x16x32_bf16 v[96:99], v[168:171], v[192:195], v[96:99]
	v_mfma_f32_16x16x32_bf16 v[92:95], v[176:179], v[192:195], v[92:95]
	v_mfma_f32_16x16x32_bf16 v[88:91], v[168:171], v[214:217], v[88:91]
	v_mfma_f32_16x16x32_bf16 v[84:87], v[176:179], v[214:217], v[84:87]
	v_mfma_f32_16x16x32_bf16 v[80:83], v[168:171], v[222:225], v[80:83]
	v_mfma_f32_16x16x32_bf16 v[76:79], v[176:179], v[222:225], v[76:79]

; #define PG8_STAGE(bufoff, gbase, voff) do { _Pragma("unroll") for (int _i = 0; _i < 2; ++_i) \
;         __builtin_amdgcn_global_load_lds((const unsigned*)((const char*)(gbase) + (voff)[_i]), (LAS unsigned*)(lds + (bufoff) + ldsw + _i * 8192), 16, 0, 0); } while (0)
; #define PG8_LDA(dst, b, h) do { _Pragma("unroll") for (int m = 0; m < 4; ++m) _Pragma("unroll") for (int k = 0; k < 2; ++k) dst[m][k] = *(const LAS bf16x8*)(lds + PG8_SA(b, h) + aoff + m * 2048 + k * 1024); } while (0)
; template <class Epi, bool ALIGN_EPI>
; __device__ __forceinline__ void gemm_phase(LAS unsigned char* lds, const Gemm g, const StaticOrder& S, const Epi& E, const int tid) {
;     ...
;             PG8_LDA(At, 1, 1); PG8_STAGE(PG8_SB(1, 0), b3, voffB); PG8_STAGE(PG8_SB(1, 1), b3 + hstepB, voffB); PG8_STAGE(PG8_SA(1, 0), a3, voffA);
	s_barrier
	s_add_u32 s42, s34, 0x8000
	s_addc_u32 s43, s35, 0
	s_add_i32 s87, s87, s56
	s_mov_b32 m0, s87
	ds_read_b128 v[180:183], v155 offset:49152
	ds_read_b128 v[184:187], v155 offset:50176
	ds_read_b128 v[188:191], v155 offset:51200
	ds_read_b128 v[192:195], v155 offset:52224


; #define PG8_STAGE(bufoff, gbase, voff) do { _Pragma("unroll") for (int _i = 0; _i < 2; ++_i) \
;         __builtin_amdgcn_global_load_lds((const unsigned*)((const char*)(gbase) + (voff)[_i]), (LAS unsigned*)(lds + (bufoff) + ldsw + _i * 8192), 16, 0, 0); } while (0)
; #define PG8_LDA(dst, b, h) do { _Pragma("unroll") for (int m = 0; m < 4; ++m) _Pragma("unroll") for (int k = 0; k < 2; ++k) dst[m][k] = *(const LAS bf16x8*)(lds + PG8_SA(b, h) + aoff + m * 2048 + k * 1024); } while (0)
; #define PG8_MMA(ai, bj, At, Bt) do { __builtin_amdgcn_s_setprio(1); _Pragma("unroll") for (int m = 0; m < 4; ++m) _Pragma("unroll") for (int n = 0; n < 2; ++n) _Pragma("unroll") for (int k = 0; k < 2; ++k) \
;         acc[ai][bj][m][n] = __builtin_amdgcn_mfma_f32_16x16x32_bf16(Bt[n][k], At[m][k], acc[ai][bj][m][n], 0, 0, 0); __builtin_amdgcn_s_setprio(0); } while (0)
; #define PG8_WAIT_V(n) asm volatile("s_waitcnt vmcnt(" #n ")" ::: "memory")
; #define PG8_WAIT_L(n) asm volatile("s_waitcnt lgkmcnt(" #n ")" ::: "memory")
; #define PG8_BAR __builtin_amdgcn_s_barrier()
; #define PG8_SCHED __builtin_amdgcn_sched_barrier(0)
; template <class Epi, bool ALIGN_EPI>
; __device__ __forceinline__ void gemm_phase(LAS unsigned char* lds, const Gemm g, const StaticOrder& S, const Epi& E, const int tid) {
;     ...
;             PG8_LDA(At, 1, 1); PG8_STAGE(PG8_SB(1, 0), b3, voffB); PG8_STAGE(PG8_SB(1, 1), b3 + hstepB, voffB); PG8_STAGE(PG8_SA(1, 0), a3, voffA);
;             PG8_WAIT_V(8); PG8_WAIT_L(0); PG8_BAR; PG8_MMA(1, 0, At, B0); PG8_MMA(1, 1, At, B1); PG8_BAR; PG8_SCHED;
	global_load_lds_dwordx4 v140, s[42:43]
	s_add_i32 m0, s87, 0x2000
	s_add_u32 s34, s34, 0xc000
	s_addc_u32 s35, s35, 0
	global_load_lds_dwordx4 v136, s[42:43]
	s_add_i32 s42, s88, s56
	s_mov_b32 m0, s42
	ds_read_b128 v[222:225], v155 offset:56320
	global_load_lds_dwordx4 v140, s[34:35]
	s_add_i32 m0, s42, 0x2000
	ds_read_b128 v[218:221], v155 offset:55296
	global_load_lds_dwordx4 v136, s[34:35]
	s_mov_b32 m0, s76
	ds_read_b128 v[214:217], v155 offset:54272
	global_load_lds_dwordx4 v142, s[22:23]
	s_mov_b32 m0, s77
	ds_read_b128 v[196:199], v155 offset:53248
	global_load_lds_dwordx4 v138, s[22:23]
	s_waitcnt vmcnt(8)
	s_waitcnt lgkmcnt(0)
	s_barrier


; #define PG8_MMA(ai, bj, At, Bt) do { __builtin_amdgcn_s_setprio(1); _Pragma("unroll") for (int m = 0; m < 4; ++m) _Pragma("unroll") for (int n = 0; n < 2; ++n) _Pragma("unroll") for (int k = 0; k < 2; ++k) \
;         acc[ai][bj][m][n] = __builtin_amdgcn_mfma_f32_16x16x32_bf16(Bt[n][k], At[m][k], acc[ai][bj][m][n], 0, 0, 0); __builtin_amdgcn_s_setprio(0); } while (0)
; #define PG8_WAIT_V(n) asm volatile("s_waitcnt vmcnt(" #n ")" ::: "memory")
; #define PG8_WAIT_L(n) asm volatile("s_waitcnt lgkmcnt(" #n ")" ::: "memory")
; #define PG8_BAR __builtin_amdgcn_s_barrier()
; #define PG8_SCHED __builtin_amdgcn_sched_barrier(0)
; template <class Epi, bool ALIGN_EPI>
; __device__ __forceinline__ void gemm_phase(LAS unsigned char* lds, const Gemm g, const StaticOrder& S, const Epi& E, const int tid) {
;     ...
;             PG8_WAIT_V(8); PG8_WAIT_L(0); PG8_BAR; PG8_MMA(1, 0, At, B0); PG8_MMA(1, 1, At, B1); PG8_BAR; PG8_SCHED;
	v_mfma_f32_16x16x32_bf16 v[24:27], v[132:135], v[180:183], v[24:27]
	v_mfma_f32_16x16x32_bf16 v[20:23], v[156:159], v[180:183], v[20:23]
	v_mfma_f32_16x16x32_bf16 v[64:67], v[132:135], v[188:191], v[64:67]
	v_mfma_f32_16x16x32_bf16 v[72:75], v[156:159], v[188:191], v[72:75]
	v_mfma_f32_16x16x32_bf16 v[16:19], v[132:135], v[196:199], v[16:19]
	v_mfma_f32_16x16x32_bf16 v[12:15], v[156:159], v[196:199], v[12:15]
	v_mfma_f32_16x16x32_bf16 v[60:63], v[132:135], v[218:221], v[60:63]
	v_mfma_f32_16x16x32_bf16 v[68:71], v[156:159], v[218:221], v[68:71]
	v_mfma_f32_16x16x32_bf16 v[24:27], v[148:151], v[184:187], v[24:27]
	v_mfma_f32_16x16x32_bf16 v[20:23], v[160:163], v[184:187], v[20:23]
	v_mfma_f32_16x16x32_bf16 v[64:67], v[148:151], v[192:195], v[64:67]
	v_mfma_f32_16x16x32_bf16 v[72:75], v[160:163], v[192:195], v[72:75]
	v_mfma_f32_16x16x32_bf16 v[16:19], v[148:151], v[214:217], v[16:19]
	v_mfma_f32_16x16x32_bf16 v[12:15], v[160:163], v[214:217], v[12:15]
	v_mfma_f32_16x16x32_bf16 v[60:63], v[148:151], v[222:225], v[60:63]
	v_mfma_f32_16x16x32_bf16 v[68:71], v[160:163], v[222:225], v[68:71]


; #define PG8_MMA(ai, bj, At, Bt) do { __builtin_amdgcn_s_setprio(1); _Pragma("unroll") for (int m = 0; m < 4; ++m) _Pragma("unroll") for (int n = 0; n < 2; ++n) _Pragma("unroll") for (int k = 0; k < 2; ++k) \
;         acc[ai][bj][m][n] = __builtin_amdgcn_mfma_f32_16x16x32_bf16(Bt[n][k], At[m][k], acc[ai][bj][m][n], 0, 0, 0); __builtin_amdgcn_s_setprio(0); } while (0)
; #define PG8_WAIT_V(n) asm volatile("s_waitcnt vmcnt(" #n ")" ::: "memory")
; #define PG8_WAIT_L(n) asm volatile("s_waitcnt lgkmcnt(" #n ")" ::: "memory")
; #define PG8_BAR __builtin_amdgcn_s_barrier()
; #define PG8_SCHED __builtin_amdgcn_sched_barrier(0)
; template <class Epi, bool ALIGN_EPI>
; __device__ __forceinline__ void gemm_phase(LAS unsigned char* lds, const Gemm g, const StaticOrder& S, const Epi& E, const int tid) {
;     ...
;             PG8_WAIT_V(8); PG8_WAIT_L(0); PG8_BAR; PG8_MMA(1, 0, At, B0); PG8_MMA(1, 1, At, B1); PG8_BAR; PG8_SCHED;
	v_mfma_f32_16x16x32_bf16 v[128:131], v[164:167], v[180:183], v[128:131]
	v_mfma_f32_16x16x32_bf16 v[124:127], v[172:175], v[180:183], v[124:127]
	v_mfma_f32_16x16x32_bf16 v[120:123], v[164:167], v[188:191], v[120:123]
	v_mfma_f32_16x16x32_bf16 v[116:119], v[172:175], v[188:191], v[116:119]
	v_mfma_f32_16x16x32_bf16 v[112:115], v[164:167], v[196:199], v[112:115]
	v_mfma_f32_16x16x32_bf16 v[108:111], v[172:175], v[196:199], v[108:111]
	v_mfma_f32_16x16x32_bf16 v[104:107], v[164:167], v[218:221], v[104:107]
	v_mfma_f32_16x16x32_bf16 v[100:103], v[172:175], v[218:221], v[100:103]
	v_mfma_f32_16x16x32_bf16 v[128:131], v[168:171], v[184:187], v[128:131]
	v_mfma_f32_16x16x32_bf16 v[124:127], v[176:179], v[184:187], v[124:127]
	v_mfma_f32_16x16x32_bf16 v[120:123], v[168:171], v[192:195], v[120:123]
	v_mfma_f32_16x16x32_bf16 v[116:119], v[176:179], v[192:195], v[116:119]
	v_mfma_f32_16x16x32_bf16 v[112:115], v[168:171], v[214:217], v[112:115]
	v_mfma_f32_16x16x32_bf16 v[108:111], v[176:179], v[214:217], v[108:111]
	v_mfma_f32_16x16x32_bf16 v[104:107], v[168:171], v[222:225], v[104:107]
	v_mfma_f32_16x16x32_bf16 v[100:103], v[176:179], v[222:225], v[100:103]

; #define LAS __attribute__((address_space(3)))
; __device__ __forceinline__ unsigned cvt_pk_bf16(float lo, float hi) { unsigned r; asm volatile("v_cvt_pk_bf16_f32 %0, %1, %2" : "=v"(r) : "v"(lo), "v"(hi)); return r; }
; #define PG8_WAIT_V(n) asm volatile("s_waitcnt vmcnt(" #n ")" ::: "memory")
; #define PG8_WAIT_L(n) asm volatile("s_waitcnt lgkmcnt(" #n ")" ::: "memory")
; #define PG8_BAR __builtin_amdgcn_s_barrier()
; #define PG8_SCHED __builtin_amdgcn_sched_barrier(0)
; template <class Epi, bool ALIGN_EPI>
; __device__ __forceinline__ void gemm_phase(LAS unsigned char* lds, const Gemm g, const StaticOrder& S, const Epi& E, const int tid) {
;     ...
;             PG8_WAIT_V(8); PG8_WAIT_L(0); PG8_BAR; PG8_MMA(1, 0, At, B0); PG8_MMA(1, 1, At, B1); PG8_BAR; PG8_SCHED;
;         }
;         if constexpr (ALIGN_EPI) { if (wr == 0) PG8_BAR; }
;     __device__ __forceinline__ void operator()(f32x4 (&acc)[2][2][4][2], const Unit& u, int wr, int wc, LAS unsigned char* lds, int& rs_pm) const {
;         int fr, fq; epi_lane(fr, fq);
;         const int row0 = u.pm * BM + wr * 64 + fr, col0 = u.pn * BM + wc * 32 + 8 * fq; u32x4 zb = zero_frag();
; #pragma unroll
;         for (int ai = 0; ai < 2; ++ai)
; #pragma unroll
;             for (int m = 0; m < 4; ++m) { float ss = 0.f;
;                 bf16* const xrow = xb + (((size_t)(u.pm * 32 + u.pn * 4 + (wc >> 1)) * BM + (wr * 64 + fr + ai * HALF + m * 16)) * 64 + (wc & 1) * 32 + 8 * fq);
; #pragma unroll
;                 for (int bj = 0; bj < 2; ++bj) {
;                     const u32x4 xw = *(const u32x4*)(xrow + (size_t)bj * (2 * BM * 64));
;                     const f32x4 x0 = (f32x4){bflo(xw.x), bfhi(xw.x), bflo(xw.y), bfhi(xw.y)}, x1 = (f32x4){bflo(xw.z), bfhi(xw.z), bflo(xw.w), bfhi(xw.w)};
;                     const f32x4 v0 = x0 + acc[ai][bj][m][0] * alpha, v1 = x1 + acc[ai][bj][m][1] * alpha; zero_acc(acc[ai][bj][m][0], zb); zero_acc(acc[ai][bj][m][1], zb);
;                     ss += (v0[0] * v0[0] + v0[1] * v0[1]) + (v0[2] * v0[2] + v0[3] * v0[3]) + (v1[0] * v1[0] + v1[1] * v1[1]) + (v1[2] * v1[2] + v1[3] * v1[3]);
;                     u32x4 w; w.x = cvt_pk_bf16(v0[0], v0[1]); w.y = cvt_pk_bf16(v0[2], v0[3]); w.z = cvt_pk_bf16(v1[0], v1[1]); w.w = cvt_pk_bf16(v1[2], v1[3]);
;                     *(u32x4*)(xrow + (size_t)bj * (2 * BM * 64)) = w; }
	s_barrier
	s_add_i32 s86, s86, 2
	s_add_u32 s84, s84, 0x10000
	s_addc_u32 s85, s85, 0
	s_add_u32 s10, s10, 0x10000
	s_addc_u32 s11, s11, 0
	s_cmpk_gt_u32 s86, 0x55
	s_cbranch_scc0 .LBB0_294
	v_and_b32_e32 v222, 15, v238
	v_lshrrev_b32_e32 v156, 4, v238
	s_lshl_b32 s100, s82, 5
	s_lshl_b32 s101, s83, 2
	v_lshlrev_b32_e32 v222, 7, v222
	s_add_i32 s100, s100, s101
	s_or_b32 s100, s100, s78
	v_lshl_or_b32 v222, v156, 4, v222
	s_ashr_i32 s101, s100, 31
	s_lshl_b64 s[100:101], s[100:101], 15
	s_add_u32 s98, s72, s100
	s_addc_u32 s99, s73, s101
	s_add_u32 s98, s98, s30
	s_addc_u32 s99, s99, s31
	s_lshl_b32 s100, s75, 7
	s_add_u32 s98, s98, s100
	s_addc_u32 s99, s99, 0
	s_lshl_b32 s100, s82, 15
	s_lshl_b32 s101, s75, 7
	s_add_i32 s100, s100, s101
	s_lshl_b32 s101, s83, 4
	s_add_i32 s100, s100, s101
	s_lshl_b32 s101, s74, 2
	s_add_i32 s100, s100, s101
	s_add_u32 s22, s44, s100
	s_addc_u32 s23, s45, 0
	global_load_dwordx4 v[176:179], v222, s[98:99]
	s_add_u32 s100, s98, 0x10000
	s_addc_u32 s101, s99, 0
	global_load_dwordx4 v[180:183], v222, s[100:101]
	global_load_dwordx4 v[184:187], v222, s[98:99] offset:2048
	s_add_u32 s100, s98, 0x10000
	s_addc_u32 s101, s99, 0
	global_load_dwordx4 v[188:191], v222, s[100:101] offset:2048
	s_add_u32 s100, s98, 0x1000
	s_addc_u32 s101, s99, 0
	global_load_dwordx4 v[192:195], v222, s[100:101]
	s_add_u32 s100, s98, 0x11000
	s_addc_u32 s101, s99, 0
	global_load_dwordx4 v[196:199], v222, s[100:101]
	s_add_u32 s100, s98, 0x1000
	s_addc_u32 s101, s99, 0
	global_load_dwordx4 v[214:217], v222, s[100:101] offset:2048
	s_add_u32 s100, s98, 0x11000
	s_addc_u32 s101, s99, 0
	global_load_dwordx4 v[218:221], v222, s[100:101] offset:2048
	s_and_b64 vcc, exec, s[46:47]
	s_cbranch_vccz .LBB0_297
	s_barrier
.LBB0_297:
	v_mov_b32_e32 v132, v1
	v_mov_b32_e32 v133, v1
	v_mov_b32_e32 v134, v1
	v_mov_b32_e32 v135, v1
	v_xor_b32_e32 v174, 16, v238
	v_xor_b32_e32 v175, 32, v238
	v_lshlrev_b32_e32 v174, 2, v174
	v_lshlrev_b32_e32 v175, 2, v175
	s_waitcnt vmcnt(7)
	v_lshlrev_b32_e32 v156, 16, v176
	v_and_b32_e32 v157, 0xffff0000, v176
	v_lshlrev_b32_e32 v158, 16, v177
	v_and_b32_e32 v159, 0xffff0000, v177
	v_lshlrev_b32_e32 v160, 16, v178
	v_and_b32_e32 v161, 0xffff0000, v178
	v_lshlrev_b32_e32 v162, 16, v179
	v_and_b32_e32 v163, 0xffff0000, v179
	v_pk_fma_f32 v[156:157], v[8:9], 0.5, v[156:157] op_sel_hi:[1,0,1]
	v_pk_fma_f32 v[158:159], v[10:11], 0.5, v[158:159] op_sel_hi:[1,0,1]
	v_pk_fma_f32 v[160:161], v[56:57], 0.5, v[160:161] op_sel_hi:[1,0,1]
	v_pk_fma_f32 v[162:163], v[58:59], 0.5, v[162:163] op_sel_hi:[1,0,1]
	v_pk_mul_f32 v[164:165], v[156:157], v[156:157]
	v_pk_fma_f32 v[164:165], v[158:159], v[158:159], v[164:165]
	v_pk_fma_f32 v[164:165], v[160:161], v[160:161], v[164:165]
	v_pk_fma_f32 v[164:165], v[162:163], v[162:163], v[164:165]
	v_mfma_f32_16x16x32_bf16 v[8:11], v[132:135], v[132:135], 0
	v_mfma_f32_16x16x32_bf16 v[56:59], v[132:135], v[132:135], 0
	v_cvt_pk_bf16_f32 v176, v156, v157
	v_cvt_pk_bf16_f32 v177, v158, v159
	v_cvt_pk_bf16_f32 v178, v160, v161
	v_cvt_pk_bf16_f32 v179, v162, v163
	global_store_dwordx4 v222, v[176:179], s[98:99]
	s_nop 0
	s_add_u32 s100, s98, 0x4000
	s_addc_u32 s101, s99, 0
	global_load_dwordx4 v[176:179], v222, s[100:101]
	s_waitcnt vmcnt(8)
	v_lshlrev_b32_e32 v156, 16, v180
	v_and_b32_e32 v157, 0xffff0000, v180
	v_lshlrev_b32_e32 v158, 16, v181
	v_and_b32_e32 v159, 0xffff0000, v181
	v_lshlrev_b32_e32 v160, 16, v182
	v_and_b32_e32 v161, 0xffff0000, v182
	v_lshlrev_b32_e32 v162, 16, v183
	v_and_b32_e32 v163, 0xffff0000, v183
	v_pk_fma_f32 v[156:157], v[4:5], 0.5, v[156:157] op_sel_hi:[1,0,1]
	v_pk_fma_f32 v[158:159], v[6:7], 0.5, v[158:159] op_sel_hi:[1,0,1]
	v_pk_fma_f32 v[160:161], v[28:29], 0.5, v[160:161] op_sel_hi:[1,0,1]
	v_pk_fma_f32 v[162:163], v[30:31], 0.5, v[162:163] op_sel_hi:[1,0,1]
	v_pk_fma_f32 v[164:165], v[156:157], v[156:157], v[164:165]
	v_pk_fma_f32 v[164:165], v[158:159], v[158:159], v[164:165]
	v_pk_fma_f32 v[164:165], v[160:161], v[160:161], v[164:165]
	v_pk_fma_f32 v[164:165], v[162:163], v[162:163], v[164:165]
	v_mfma_f32_16x16x32_bf16 v[4:7], v[132:135], v[132:135], 0
	v_mfma_f32_16x16x32_bf16 v[28:31], v[132:135], v[132:135], 0
	v_cvt_pk_bf16_f32 v180, v156, v157
	v_cvt_pk_bf16_f32 v181, v158, v159
	v_cvt_pk_bf16_f32 v182, v160, v161
	v_cvt_pk_bf16_f32 v183, v162, v163
	s_add_u32 s100, s98, 0x10000
	s_addc_u32 s101, s99, 0
	global_store_dwordx4 v222, v[180:183], s[100:101]
	v_add_f32_e32 v166, v164, v165
	s_add_u32 s100, s98, 0x14000
	s_addc_u32 s101, s99, 0
	global_load_dwordx4 v[180:183], v222, s[100:101]
	s_waitcnt vmcnt(9)
	v_lshlrev_b32_e32 v156, 16, v184
	v_and_b32_e32 v157, 0xffff0000, v184
	v_lshlrev_b32_e32 v158, 16, v185
	v_and_b32_e32 v159, 0xffff0000, v185
	v_lshlrev_b32_e32 v160, 16, v186
	v_and_b32_e32 v161, 0xffff0000, v186
	v_lshlrev_b32_e32 v162, 16, v187
	v_and_b32_e32 v163, 0xffff0000, v187
	v_pk_fma_f32 v[156:157], v[52:53], 0.5, v[156:157] op_sel_hi:[1,0,1]
	v_pk_fma_f32 v[158:159], v[54:55], 0.5, v[158:159] op_sel_hi:[1,0,1]
	v_pk_fma_f32 v[160:161], v[48:49], 0.5, v[160:161] op_sel_hi:[1,0,1]
	v_pk_fma_f32 v[162:163], v[50:51], 0.5, v[162:163] op_sel_hi:[1,0,1]
	v_pk_mul_f32 v[164:165], v[156:157], v[156:157]
	v_pk_fma_f32 v[164:165], v[158:159], v[158:159], v[164:165]
	v_pk_fma_f32 v[164:165], v[160:161], v[160:161], v[164:165]
	v_pk_fma_f32 v[164:165], v[162:163], v[162:163], v[164:165]
	v_mfma_f32_16x16x32_bf16 v[52:55], v[132:135], v[132:135], 0
	v_mfma_f32_16x16x32_bf16 v[48:51], v[132:135], v[132:135], 0
	v_cvt_pk_bf16_f32 v184, v156, v157
	v_cvt_pk_bf16_f32 v185, v158, v159
	v_cvt_pk_bf16_f32 v186, v160, v161
	v_cvt_pk_bf16_f32 v187, v162, v163
	global_store_dwordx4 v222, v[184:187], s[98:99] offset:2048
	s_nop 0
	s_add_u32 s100, s98, 0x4000
	s_addc_u32 s101, s99, 0
	global_load_dwordx4 v[184:187], v222, s[100:101] offset:2048
	s_waitcnt vmcnt(10)
; __device__ __forceinline__ unsigned cvt_pk_bf16(float lo, float hi) { unsigned r; asm volatile("v_cvt_pk_bf16_f32 %0, %1, %2" : "=v"(r) : "v"(lo), "v"(hi)); return r; }
;     __device__ __forceinline__ void operator()(f32x4 (&acc)[2][2][4][2], const Unit& u, int wr, int wc, LAS unsigned char* lds, int& rs_pm) const {
;     ...
;             for (int m = 0; m < 4; ++m) { float ss = 0.f;
;                 bf16* const xrow = xb + (((size_t)(u.pm * 32 + u.pn * 4 + (wc >> 1)) * BM + (wr * 64 + fr + ai * HALF + m * 16)) * 64 + (wc & 1) * 32 + 8 * fq);
; #pragma unroll
;                 for (int bj = 0; bj < 2; ++bj) {
;                     const u32x4 xw = *(const u32x4*)(xrow + (size_t)bj * (2 * BM * 64));
;                     const f32x4 x0 = (f32x4){bflo(xw.x), bfhi(xw.x), bflo(xw.y), bfhi(xw.y)}, x1 = (f32x4){bflo(xw.z), bfhi(xw.z), bflo(xw.w), bfhi(xw.w)};
;                     const f32x4 v0 = x0 + acc[ai][bj][m][0] * alpha, v1 = x1 + acc[ai][bj][m][1] * alpha; zero_acc(acc[ai][bj][m][0], zb); zero_acc(acc[ai][bj][m][1], zb);
;                     ss += (v0[0] * v0[0] + v0[1] * v0[1]) + (v0[2] * v0[2] + v0[3] * v0[3]) + (v1[0] * v1[0] + v1[1] * v1[1]) + (v1[2] * v1[2] + v1[3] * v1[3]);
;                     u32x4 w; w.x = cvt_pk_bf16(v0[0], v0[1]); w.y = cvt_pk_bf16(v0[2], v0[3]); w.z = cvt_pk_bf16(v1[0], v1[1]); w.w = cvt_pk_bf16(v1[2], v1[3]);
;                     *(u32x4*)(xrow + (size_t)bj * (2 * BM * 64)) = w; }
	v_lshlrev_b32_e32 v156, 16, v188
	v_and_b32_e32 v157, 0xffff0000, v188
	v_lshlrev_b32_e32 v158, 16, v189
	v_and_b32_e32 v159, 0xffff0000, v189
	v_lshlrev_b32_e32 v160, 16, v190
	v_and_b32_e32 v161, 0xffff0000, v190
	v_lshlrev_b32_e32 v162, 16, v191
	v_and_b32_e32 v163, 0xffff0000, v191
	v_pk_fma_f32 v[156:157], v[96:97], 0.5, v[156:157] op_sel_hi:[1,0,1]
	v_pk_fma_f32 v[158:159], v[98:99], 0.5, v[158:159] op_sel_hi:[1,0,1]
	v_pk_fma_f32 v[160:161], v[92:93], 0.5, v[160:161] op_sel_hi:[1,0,1]
	v_pk_fma_f32 v[162:163], v[94:95], 0.5, v[162:163] op_sel_hi:[1,0,1]
	v_pk_fma_f32 v[164:165], v[156:157], v[156:157], v[164:165]
	v_pk_fma_f32 v[164:165], v[158:159], v[158:159], v[164:165]
	v_pk_fma_f32 v[164:165], v[160:161], v[160:161], v[164:165]
	v_pk_fma_f32 v[164:165], v[162:163], v[162:163], v[164:165]
	v_mfma_f32_16x16x32_bf16 v[96:99], v[132:135], v[132:135], 0
	v_mfma_f32_16x16x32_bf16 v[92:95], v[132:135], v[132:135], 0
	v_cvt_pk_bf16_f32 v188, v156, v157
	v_cvt_pk_bf16_f32 v189, v158, v159
	v_cvt_pk_bf16_f32 v190, v160, v161
	v_cvt_pk_bf16_f32 v191, v162, v163
	s_add_u32 s100, s98, 0x10000
	s_addc_u32 s101, s99, 0
	global_store_dwordx4 v222, v[188:191], s[100:101] offset:2048
	v_add_f32_e32 v167, v164, v165
	s_add_u32 s100, s98, 0x14000
	s_addc_u32 s101, s99, 0
	global_load_dwordx4 v[188:191], v222, s[100:101] offset:2048
	s_waitcnt vmcnt(11)
	v_lshlrev_b32_e32 v156, 16, v192
	v_and_b32_e32 v157, 0xffff0000, v192
	v_lshlrev_b32_e32 v158, 16, v193
	v_and_b32_e32 v159, 0xffff0000, v193
	v_lshlrev_b32_e32 v160, 16, v194
	v_and_b32_e32 v161, 0xffff0000, v194
	v_lshlrev_b32_e32 v162, 16, v195
	v_and_b32_e32 v163, 0xffff0000, v195
	v_pk_fma_f32 v[156:157], v[44:45], 0.5, v[156:157] op_sel_hi:[1,0,1]
	v_pk_fma_f32 v[158:159], v[46:47], 0.5, v[158:159] op_sel_hi:[1,0,1]
	v_pk_fma_f32 v[160:161], v[40:41], 0.5, v[160:161] op_sel_hi:[1,0,1]
	v_pk_fma_f32 v[162:163], v[42:43], 0.5, v[162:163] op_sel_hi:[1,0,1]
	v_pk_mul_f32 v[164:165], v[156:157], v[156:157]
	v_pk_fma_f32 v[164:165], v[158:159], v[158:159], v[164:165]
	v_pk_fma_f32 v[164:165], v[160:161], v[160:161], v[164:165]
	v_pk_fma_f32 v[164:165], v[162:163], v[162:163], v[164:165]
	v_mfma_f32_16x16x32_bf16 v[44:47], v[132:135], v[132:135], 0
	v_mfma_f32_16x16x32_bf16 v[40:43], v[132:135], v[132:135], 0
	v_cvt_pk_bf16_f32 v192, v156, v157
	v_cvt_pk_bf16_f32 v193, v158, v159
	v_cvt_pk_bf16_f32 v194, v160, v161
	v_cvt_pk_bf16_f32 v195, v162, v163
	s_add_u32 s100, s98, 0x1000
	s_addc_u32 s101, s99, 0
	global_store_dwordx4 v222, v[192:195], s[100:101]
	s_nop 0
	s_add_u32 s100, s98, 0x5000
	s_addc_u32 s101, s99, 0
	global_load_dwordx4 v[192:195], v222, s[100:101]
	s_waitcnt vmcnt(12)
	v_lshlrev_b32_e32 v156, 16, v196
	v_and_b32_e32 v157, 0xffff0000, v196
	v_lshlrev_b32_e32 v158, 16, v197
	v_and_b32_e32 v159, 0xffff0000, v197
	v_lshlrev_b32_e32 v160, 16, v198
	v_and_b32_e32 v161, 0xffff0000, v198
	v_lshlrev_b32_e32 v162, 16, v199
	v_and_b32_e32 v163, 0xffff0000, v199
	v_pk_fma_f32 v[156:157], v[88:89], 0.5, v[156:157] op_sel_hi:[1,0,1]
	v_pk_fma_f32 v[158:159], v[90:91], 0.5, v[158:159] op_sel_hi:[1,0,1]
	v_pk_fma_f32 v[160:161], v[84:85], 0.5, v[160:161] op_sel_hi:[1,0,1]
	v_pk_fma_f32 v[162:163], v[86:87], 0.5, v[162:163] op_sel_hi:[1,0,1]
	v_pk_fma_f32 v[164:165], v[156:157], v[156:157], v[164:165]
	v_pk_fma_f32 v[164:165], v[158:159], v[158:159], v[164:165]
	v_pk_fma_f32 v[164:165], v[160:161], v[160:161], v[164:165]
	v_pk_fma_f32 v[164:165], v[162:163], v[162:163], v[164:165]
	v_mfma_f32_16x16x32_bf16 v[88:91], v[132:135], v[132:135], 0
	v_mfma_f32_16x16x32_bf16 v[84:87], v[132:135], v[132:135], 0
	v_cvt_pk_bf16_f32 v196, v156, v157
	v_cvt_pk_bf16_f32 v197, v158, v159
	v_cvt_pk_bf16_f32 v198, v160, v161
	v_cvt_pk_bf16_f32 v199, v162, v163
	s_add_u32 s100, s98, 0x11000
	s_addc_u32 s101, s99, 0
	global_store_dwordx4 v222, v[196:199], s[100:101]
	v_add_f32_e32 v168, v164, v165
	s_add_u32 s100, s98, 0x15000
	s_addc_u32 s101, s99, 0
	global_load_dwordx4 v[196:199], v222, s[100:101]
	s_waitcnt vmcnt(13)
	v_lshlrev_b32_e32 v156, 16, v214
	v_and_b32_e32 v157, 0xffff0000, v214
	v_lshlrev_b32_e32 v158, 16, v215
	v_and_b32_e32 v159, 0xffff0000, v215
	v_lshlrev_b32_e32 v160, 16, v216
	v_and_b32_e32 v161, 0xffff0000, v216
	v_lshlrev_b32_e32 v162, 16, v217
	v_and_b32_e32 v163, 0xffff0000, v217
	v_pk_fma_f32 v[156:157], v[36:37], 0.5, v[156:157] op_sel_hi:[1,0,1]
	v_pk_fma_f32 v[158:159], v[38:39], 0.5, v[158:159] op_sel_hi:[1,0,1]
	v_pk_fma_f32 v[160:161], v[32:33], 0.5, v[160:161] op_sel_hi:[1,0,1]
	v_pk_fma_f32 v[162:163], v[34:35], 0.5, v[162:163] op_sel_hi:[1,0,1]
	v_pk_mul_f32 v[164:165], v[156:157], v[156:157]
	v_pk_fma_f32 v[164:165], v[158:159], v[158:159], v[164:165]
	v_pk_fma_f32 v[164:165], v[160:161], v[160:161], v[164:165]
	v_pk_fma_f32 v[164:165], v[162:163], v[162:163], v[164:165]
	v_mfma_f32_16x16x32_bf16 v[36:39], v[132:135], v[132:135], 0
	v_mfma_f32_16x16x32_bf16 v[32:35], v[132:135], v[132:135], 0
	v_cvt_pk_bf16_f32 v214, v156, v157
	v_cvt_pk_bf16_f32 v215, v158, v159
	v_cvt_pk_bf16_f32 v216, v160, v161
	v_cvt_pk_bf16_f32 v217, v162, v163
	s_add_u32 s100, s98, 0x1000
	s_addc_u32 s101, s99, 0
	global_store_dwordx4 v222, v[214:217], s[100:101] offset:2048
	s_nop 0
	s_add_u32 s100, s98, 0x5000
	s_addc_u32 s101, s99, 0
	global_load_dwordx4 v[214:217], v222, s[100:101] offset:2048
	s_waitcnt vmcnt(14)
; __device__ __forceinline__ unsigned cvt_pk_bf16(float lo, float hi) { unsigned r; asm volatile("v_cvt_pk_bf16_f32 %0, %1, %2" : "=v"(r) : "v"(lo), "v"(hi)); return r; }
;     __device__ __forceinline__ void operator()(f32x4 (&acc)[2][2][4][2], const Unit& u, int wr, int wc, LAS unsigned char* lds, int& rs_pm) const {
;     ...
;             for (int m = 0; m < 4; ++m) { float ss = 0.f;
;                 bf16* const xrow = xb + (((size_t)(u.pm * 32 + u.pn * 4 + (wc >> 1)) * BM + (wr * 64 + fr + ai * HALF + m * 16)) * 64 + (wc & 1) * 32 + 8 * fq);
; #pragma unroll
;                 for (int bj = 0; bj < 2; ++bj) {
;                     const u32x4 xw = *(const u32x4*)(xrow + (size_t)bj * (2 * BM * 64));
;                     const f32x4 x0 = (f32x4){bflo(xw.x), bfhi(xw.x), bflo(xw.y), bfhi(xw.y)}, x1 = (f32x4){bflo(xw.z), bfhi(xw.z), bflo(xw.w), bfhi(xw.w)};
;                     const f32x4 v0 = x0 + acc[ai][bj][m][0] * alpha, v1 = x1 + acc[ai][bj][m][1] * alpha; zero_acc(acc[ai][bj][m][0], zb); zero_acc(acc[ai][bj][m][1], zb);
;                     ss += (v0[0] * v0[0] + v0[1] * v0[1]) + (v0[2] * v0[2] + v0[3] * v0[3]) + (v1[0] * v1[0] + v1[1] * v1[1]) + (v1[2] * v1[2] + v1[3] * v1[3]);
;                     u32x4 w; w.x = cvt_pk_bf16(v0[0], v0[1]); w.y = cvt_pk_bf16(v0[2], v0[3]); w.z = cvt_pk_bf16(v1[0], v1[1]); w.w = cvt_pk_bf16(v1[2], v1[3]);
;                     *(u32x4*)(xrow + (size_t)bj * (2 * BM * 64)) = w; }
	v_lshlrev_b32_e32 v156, 16, v218
	v_and_b32_e32 v157, 0xffff0000, v218
	v_lshlrev_b32_e32 v158, 16, v219
	v_and_b32_e32 v159, 0xffff0000, v219
	v_lshlrev_b32_e32 v160, 16, v220
	v_and_b32_e32 v161, 0xffff0000, v220
	v_lshlrev_b32_e32 v162, 16, v221
	v_and_b32_e32 v163, 0xffff0000, v221
	v_pk_fma_f32 v[156:157], v[80:81], 0.5, v[156:157] op_sel_hi:[1,0,1]
	v_pk_fma_f32 v[158:159], v[82:83], 0.5, v[158:159] op_sel_hi:[1,0,1]
	v_pk_fma_f32 v[160:161], v[76:77], 0.5, v[160:161] op_sel_hi:[1,0,1]
	v_pk_fma_f32 v[162:163], v[78:79], 0.5, v[162:163] op_sel_hi:[1,0,1]
	v_pk_fma_f32 v[164:165], v[156:157], v[156:157], v[164:165]
	v_pk_fma_f32 v[164:165], v[158:159], v[158:159], v[164:165]
	v_pk_fma_f32 v[164:165], v[160:161], v[160:161], v[164:165]
	v_pk_fma_f32 v[164:165], v[162:163], v[162:163], v[164:165]
	v_mfma_f32_16x16x32_bf16 v[80:83], v[132:135], v[132:135], 0
	v_mfma_f32_16x16x32_bf16 v[76:79], v[132:135], v[132:135], 0
	v_cvt_pk_bf16_f32 v218, v156, v157
	v_cvt_pk_bf16_f32 v219, v158, v159
	v_cvt_pk_bf16_f32 v220, v160, v161
	v_cvt_pk_bf16_f32 v221, v162, v163
	s_add_u32 s100, s98, 0x11000
	s_addc_u32 s101, s99, 0
	global_store_dwordx4 v222, v[218:221], s[100:101] offset:2048
	v_add_f32_e32 v169, v164, v165
	s_add_u32 s100, s98, 0x15000
	s_addc_u32 s101, s99, 0
	global_load_dwordx4 v[218:221], v222, s[100:101] offset:2048
	s_waitcnt vmcnt(14)
	v_lshlrev_b32_e32 v156, 16, v176
	v_and_b32_e32 v157, 0xffff0000, v176
	v_lshlrev_b32_e32 v158, 16, v177
	v_and_b32_e32 v159, 0xffff0000, v177
	v_lshlrev_b32_e32 v160, 16, v178
	v_and_b32_e32 v161, 0xffff0000, v178
	v_lshlrev_b32_e32 v162, 16, v179
	v_and_b32_e32 v163, 0xffff0000, v179
	v_pk_fma_f32 v[156:157], v[24:25], 0.5, v[156:157] op_sel_hi:[1,0,1]
	v_pk_fma_f32 v[158:159], v[26:27], 0.5, v[158:159] op_sel_hi:[1,0,1]
	v_pk_fma_f32 v[160:161], v[20:21], 0.5, v[160:161] op_sel_hi:[1,0,1]
	v_pk_fma_f32 v[162:163], v[22:23], 0.5, v[162:163] op_sel_hi:[1,0,1]
	v_pk_mul_f32 v[164:165], v[156:157], v[156:157]
	v_pk_fma_f32 v[164:165], v[158:159], v[158:159], v[164:165]
	v_pk_fma_f32 v[164:165], v[160:161], v[160:161], v[164:165]
	v_pk_fma_f32 v[164:165], v[162:163], v[162:163], v[164:165]
	v_mfma_f32_16x16x32_bf16 v[24:27], v[132:135], v[132:135], 0
	v_mfma_f32_16x16x32_bf16 v[20:23], v[132:135], v[132:135], 0
	v_cvt_pk_bf16_f32 v176, v156, v157
	v_cvt_pk_bf16_f32 v177, v158, v159
	v_cvt_pk_bf16_f32 v178, v160, v161
	v_cvt_pk_bf16_f32 v179, v162, v163
	s_add_u32 s100, s98, 0x4000
	s_addc_u32 s101, s99, 0
	global_store_dwordx4 v222, v[176:179], s[100:101]
	s_nop 0
	s_waitcnt vmcnt(13)
	v_lshlrev_b32_e32 v156, 16, v180
	v_and_b32_e32 v157, 0xffff0000, v180
	v_lshlrev_b32_e32 v158, 16, v181
	v_and_b32_e32 v159, 0xffff0000, v181
	v_lshlrev_b32_e32 v160, 16, v182
	v_and_b32_e32 v161, 0xffff0000, v182
	v_lshlrev_b32_e32 v162, 16, v183
	v_and_b32_e32 v163, 0xffff0000, v183
	v_pk_fma_f32 v[156:157], v[128:129], 0.5, v[156:157] op_sel_hi:[1,0,1]
	v_pk_fma_f32 v[158:159], v[130:131], 0.5, v[158:159] op_sel_hi:[1,0,1]
	v_pk_fma_f32 v[160:161], v[124:125], 0.5, v[160:161] op_sel_hi:[1,0,1]
	v_pk_fma_f32 v[162:163], v[126:127], 0.5, v[162:163] op_sel_hi:[1,0,1]
	v_pk_fma_f32 v[164:165], v[156:157], v[156:157], v[164:165]
	v_pk_fma_f32 v[164:165], v[158:159], v[158:159], v[164:165]
	v_pk_fma_f32 v[164:165], v[160:161], v[160:161], v[164:165]
	v_pk_fma_f32 v[164:165], v[162:163], v[162:163], v[164:165]
	v_mfma_f32_16x16x32_bf16 v[128:131], v[132:135], v[132:135], 0
	v_mfma_f32_16x16x32_bf16 v[124:127], v[132:135], v[132:135], 0
	v_cvt_pk_bf16_f32 v180, v156, v157
	v_cvt_pk_bf16_f32 v181, v158, v159
	v_cvt_pk_bf16_f32 v182, v160, v161
	v_cvt_pk_bf16_f32 v183, v162, v163
	s_add_u32 s100, s98, 0x14000
	s_addc_u32 s101, s99, 0
	global_store_dwordx4 v222, v[180:183], s[100:101]
	v_add_f32_e32 v170, v164, v165
	s_waitcnt vmcnt(12)
	v_lshlrev_b32_e32 v156, 16, v184
	v_and_b32_e32 v157, 0xffff0000, v184
	v_lshlrev_b32_e32 v158, 16, v185
	v_and_b32_e32 v159, 0xffff0000, v185
	v_lshlrev_b32_e32 v160, 16, v186
	v_and_b32_e32 v161, 0xffff0000, v186
	v_lshlrev_b32_e32 v162, 16, v187
	v_and_b32_e32 v163, 0xffff0000, v187
	v_pk_fma_f32 v[156:157], v[64:65], 0.5, v[156:157] op_sel_hi:[1,0,1]
	v_pk_fma_f32 v[158:159], v[66:67], 0.5, v[158:159] op_sel_hi:[1,0,1]
	v_pk_fma_f32 v[160:161], v[72:73], 0.5, v[160:161] op_sel_hi:[1,0,1]
	v_pk_fma_f32 v[162:163], v[74:75], 0.5, v[162:163] op_sel_hi:[1,0,1]
	v_pk_mul_f32 v[164:165], v[156:157], v[156:157]
	v_pk_fma_f32 v[164:165], v[158:159], v[158:159], v[164:165]
	v_pk_fma_f32 v[164:165], v[160:161], v[160:161], v[164:165]
	v_pk_fma_f32 v[164:165], v[162:163], v[162:163], v[164:165]
	v_mfma_f32_16x16x32_bf16 v[64:67], v[132:135], v[132:135], 0
	v_mfma_f32_16x16x32_bf16 v[72:75], v[132:135], v[132:135], 0
	v_cvt_pk_bf16_f32 v184, v156, v157
	v_cvt_pk_bf16_f32 v185, v158, v159
	v_cvt_pk_bf16_f32 v186, v160, v161
	v_cvt_pk_bf16_f32 v187, v162, v163
	s_add_u32 s100, s98, 0x4000
	s_addc_u32 s101, s99, 0
	global_store_dwordx4 v222, v[184:187], s[100:101] offset:2048
	s_nop 0
	s_waitcnt vmcnt(11)
; __device__ __forceinline__ unsigned cvt_pk_bf16(float lo, float hi) { unsigned r; asm volatile("v_cvt_pk_bf16_f32 %0, %1, %2" : "=v"(r) : "v"(lo), "v"(hi)); return r; }
;     __device__ __forceinline__ void operator()(f32x4 (&acc)[2][2][4][2], const Unit& u, int wr, int wc, LAS unsigned char* lds, int& rs_pm) const {
;     ...
;             for (int m = 0; m < 4; ++m) { float ss = 0.f;
;                 bf16* const xrow = xb + (((size_t)(u.pm * 32 + u.pn * 4 + (wc >> 1)) * BM + (wr * 64 + fr + ai * HALF + m * 16)) * 64 + (wc & 1) * 32 + 8 * fq);
; #pragma unroll
;                 for (int bj = 0; bj < 2; ++bj) {
;                     const u32x4 xw = *(const u32x4*)(xrow + (size_t)bj * (2 * BM * 64));
;                     const f32x4 x0 = (f32x4){bflo(xw.x), bfhi(xw.x), bflo(xw.y), bfhi(xw.y)}, x1 = (f32x4){bflo(xw.z), bfhi(xw.z), bflo(xw.w), bfhi(xw.w)};
;                     const f32x4 v0 = x0 + acc[ai][bj][m][0] * alpha, v1 = x1 + acc[ai][bj][m][1] * alpha; zero_acc(acc[ai][bj][m][0], zb); zero_acc(acc[ai][bj][m][1], zb);
;                     ss += (v0[0] * v0[0] + v0[1] * v0[1]) + (v0[2] * v0[2] + v0[3] * v0[3]) + (v1[0] * v1[0] + v1[1] * v1[1]) + (v1[2] * v1[2] + v1[3] * v1[3]);
;                     u32x4 w; w.x = cvt_pk_bf16(v0[0], v0[1]); w.y = cvt_pk_bf16(v0[2], v0[3]); w.z = cvt_pk_bf16(v1[0], v1[1]); w.w = cvt_pk_bf16(v1[2], v1[3]);
;                     *(u32x4*)(xrow + (size_t)bj * (2 * BM * 64)) = w; }
	v_lshlrev_b32_e32 v156, 16, v188
	v_and_b32_e32 v157, 0xffff0000, v188
	v_lshlrev_b32_e32 v158, 16, v189
	v_and_b32_e32 v159, 0xffff0000, v189
	v_lshlrev_b32_e32 v160, 16, v190
	v_and_b32_e32 v161, 0xffff0000, v190
	v_lshlrev_b32_e32 v162, 16, v191
	v_and_b32_e32 v163, 0xffff0000, v191
	v_pk_fma_f32 v[156:157], v[120:121], 0.5, v[156:157] op_sel_hi:[1,0,1]
	v_pk_fma_f32 v[158:159], v[122:123], 0.5, v[158:159] op_sel_hi:[1,0,1]
	v_pk_fma_f32 v[160:161], v[116:117], 0.5, v[160:161] op_sel_hi:[1,0,1]
	v_pk_fma_f32 v[162:163], v[118:119], 0.5, v[162:163] op_sel_hi:[1,0,1]
	v_pk_fma_f32 v[164:165], v[156:157], v[156:157], v[164:165]
	v_pk_fma_f32 v[164:165], v[158:159], v[158:159], v[164:165]
	v_pk_fma_f32 v[164:165], v[160:161], v[160:161], v[164:165]
	v_pk_fma_f32 v[164:165], v[162:163], v[162:163], v[164:165]
	v_mfma_f32_16x16x32_bf16 v[120:123], v[132:135], v[132:135], 0
	v_mfma_f32_16x16x32_bf16 v[116:119], v[132:135], v[132:135], 0
	v_cvt_pk_bf16_f32 v188, v156, v157
	v_cvt_pk_bf16_f32 v189, v158, v159
	v_cvt_pk_bf16_f32 v190, v160, v161
	v_cvt_pk_bf16_f32 v191, v162, v163
	s_add_u32 s100, s98, 0x14000
	s_addc_u32 s101, s99, 0
	global_store_dwordx4 v222, v[188:191], s[100:101] offset:2048
	v_add_f32_e32 v171, v164, v165
	s_waitcnt vmcnt(10)
	v_lshlrev_b32_e32 v156, 16, v192
	v_and_b32_e32 v157, 0xffff0000, v192
	v_lshlrev_b32_e32 v158, 16, v193
	v_and_b32_e32 v159, 0xffff0000, v193
	v_lshlrev_b32_e32 v160, 16, v194
	v_and_b32_e32 v161, 0xffff0000, v194
	v_lshlrev_b32_e32 v162, 16, v195
	v_and_b32_e32 v163, 0xffff0000, v195
	v_pk_fma_f32 v[156:157], v[16:17], 0.5, v[156:157] op_sel_hi:[1,0,1]
	v_pk_fma_f32 v[158:159], v[18:19], 0.5, v[158:159] op_sel_hi:[1,0,1]
	v_pk_fma_f32 v[160:161], v[12:13], 0.5, v[160:161] op_sel_hi:[1,0,1]
	v_pk_fma_f32 v[162:163], v[14:15], 0.5, v[162:163] op_sel_hi:[1,0,1]
	v_pk_mul_f32 v[164:165], v[156:157], v[156:157]
	v_pk_fma_f32 v[164:165], v[158:159], v[158:159], v[164:165]
	v_pk_fma_f32 v[164:165], v[160:161], v[160:161], v[164:165]
	v_pk_fma_f32 v[164:165], v[162:163], v[162:163], v[164:165]
	v_mfma_f32_16x16x32_bf16 v[16:19], v[132:135], v[132:135], 0
	v_mfma_f32_16x16x32_bf16 v[12:15], v[132:135], v[132:135], 0
	v_cvt_pk_bf16_f32 v192, v156, v157
	v_cvt_pk_bf16_f32 v193, v158, v159
	v_cvt_pk_bf16_f32 v194, v160, v161
	v_cvt_pk_bf16_f32 v195, v162, v163
	s_add_u32 s100, s98, 0x5000
	s_addc_u32 s101, s99, 0
	global_store_dwordx4 v222, v[192:195], s[100:101]
	s_nop 0
	s_waitcnt vmcnt(9)
	v_lshlrev_b32_e32 v156, 16, v196
	v_and_b32_e32 v157, 0xffff0000, v196
	v_lshlrev_b32_e32 v158, 16, v197
	v_and_b32_e32 v159, 0xffff0000, v197
	v_lshlrev_b32_e32 v160, 16, v198
	v_and_b32_e32 v161, 0xffff0000, v198
	v_lshlrev_b32_e32 v162, 16, v199
	v_and_b32_e32 v163, 0xffff0000, v199
	v_pk_fma_f32 v[156:157], v[112:113], 0.5, v[156:157] op_sel_hi:[1,0,1]
	v_pk_fma_f32 v[158:159], v[114:115], 0.5, v[158:159] op_sel_hi:[1,0,1]
	v_pk_fma_f32 v[160:161], v[108:109], 0.5, v[160:161] op_sel_hi:[1,0,1]
	v_pk_fma_f32 v[162:163], v[110:111], 0.5, v[162:163] op_sel_hi:[1,0,1]
	v_pk_fma_f32 v[164:165], v[156:157], v[156:157], v[164:165]
	v_pk_fma_f32 v[164:165], v[158:159], v[158:159], v[164:165]
	v_pk_fma_f32 v[164:165], v[160:161], v[160:161], v[164:165]
	v_pk_fma_f32 v[164:165], v[162:163], v[162:163], v[164:165]
	v_mfma_f32_16x16x32_bf16 v[112:115], v[132:135], v[132:135], 0
	v_mfma_f32_16x16x32_bf16 v[108:111], v[132:135], v[132:135], 0
	v_cvt_pk_bf16_f32 v196, v156, v157
	v_cvt_pk_bf16_f32 v197, v158, v159
	v_cvt_pk_bf16_f32 v198, v160, v161
	v_cvt_pk_bf16_f32 v199, v162, v163
	s_add_u32 s100, s98, 0x15000
	s_addc_u32 s101, s99, 0
	global_store_dwordx4 v222, v[196:199], s[100:101]
	v_add_f32_e32 v172, v164, v165
	s_waitcnt vmcnt(8)
; __device__ __forceinline__ unsigned cvt_pk_bf16(float lo, float hi) { unsigned r; asm volatile("v_cvt_pk_bf16_f32 %0, %1, %2" : "=v"(r) : "v"(lo), "v"(hi)); return r; }
;     __device__ __forceinline__ void operator()(f32x4 (&acc)[2][2][4][2], const Unit& u, int wr, int wc, LAS unsigned char* lds, int& rs_pm) const {
;     ...
;             for (int m = 0; m < 4; ++m) { float ss = 0.f;
;                 bf16* const xrow = xb + (((size_t)(u.pm * 32 + u.pn * 4 + (wc >> 1)) * BM + (wr * 64 + fr + ai * HALF + m * 16)) * 64 + (wc & 1) * 32 + 8 * fq);
; #pragma unroll
;                 for (int bj = 0; bj < 2; ++bj) {
;                     const u32x4 xw = *(const u32x4*)(xrow + (size_t)bj * (2 * BM * 64));
;                     const f32x4 x0 = (f32x4){bflo(xw.x), bfhi(xw.x), bflo(xw.y), bfhi(xw.y)}, x1 = (f32x4){bflo(xw.z), bfhi(xw.z), bflo(xw.w), bfhi(xw.w)};
;                     const f32x4 v0 = x0 + acc[ai][bj][m][0] * alpha, v1 = x1 + acc[ai][bj][m][1] * alpha; zero_acc(acc[ai][bj][m][0], zb); zero_acc(acc[ai][bj][m][1], zb);
;                     ss += (v0[0] * v0[0] + v0[1] * v0[1]) + (v0[2] * v0[2] + v0[3] * v0[3]) + (v1[0] * v1[0] + v1[1] * v1[1]) + (v1[2] * v1[2] + v1[3] * v1[3]);
;                     u32x4 w; w.x = cvt_pk_bf16(v0[0], v0[1]); w.y = cvt_pk_bf16(v0[2], v0[3]); w.z = cvt_pk_bf16(v1[0], v1[1]); w.w = cvt_pk_bf16(v1[2], v1[3]);
;                     *(u32x4*)(xrow + (size_t)bj * (2 * BM * 64)) = w; }
;                 ss += __shfl_xor(ss, 16); ss += __shfl_xor(ss, 32);
;                 if (fq == 0) part[(size_t)(row0 + ai * HALF + m * 16) * 32 + u.pn * 4 + wc] = ss;
;                 asm volatile("" ::: "memory"); }
	v_lshlrev_b32_e32 v156, 16, v214
	v_and_b32_e32 v157, 0xffff0000, v214
	v_lshlrev_b32_e32 v158, 16, v215
	v_and_b32_e32 v159, 0xffff0000, v215
	v_lshlrev_b32_e32 v160, 16, v216
	v_and_b32_e32 v161, 0xffff0000, v216
	v_lshlrev_b32_e32 v162, 16, v217
	v_and_b32_e32 v163, 0xffff0000, v217
	v_pk_fma_f32 v[156:157], v[60:61], 0.5, v[156:157] op_sel_hi:[1,0,1]
	v_pk_fma_f32 v[158:159], v[62:63], 0.5, v[158:159] op_sel_hi:[1,0,1]
	v_pk_fma_f32 v[160:161], v[68:69], 0.5, v[160:161] op_sel_hi:[1,0,1]
	v_pk_fma_f32 v[162:163], v[70:71], 0.5, v[162:163] op_sel_hi:[1,0,1]
	v_pk_mul_f32 v[164:165], v[156:157], v[156:157]
	v_pk_fma_f32 v[164:165], v[158:159], v[158:159], v[164:165]
	v_pk_fma_f32 v[164:165], v[160:161], v[160:161], v[164:165]
	v_pk_fma_f32 v[164:165], v[162:163], v[162:163], v[164:165]
	v_mfma_f32_16x16x32_bf16 v[60:63], v[132:135], v[132:135], 0
	v_mfma_f32_16x16x32_bf16 v[68:71], v[132:135], v[132:135], 0
	v_cvt_pk_bf16_f32 v214, v156, v157
	v_cvt_pk_bf16_f32 v215, v158, v159
	v_cvt_pk_bf16_f32 v216, v160, v161
	v_cvt_pk_bf16_f32 v217, v162, v163
	s_add_u32 s100, s98, 0x5000
	s_addc_u32 s101, s99, 0
	global_store_dwordx4 v222, v[214:217], s[100:101] offset:2048
	s_nop 0
	s_waitcnt vmcnt(7)
	v_lshlrev_b32_e32 v156, 16, v218
	v_and_b32_e32 v157, 0xffff0000, v218
	v_lshlrev_b32_e32 v158, 16, v219
	v_and_b32_e32 v159, 0xffff0000, v219
	v_lshlrev_b32_e32 v160, 16, v220
	v_and_b32_e32 v161, 0xffff0000, v220
	v_lshlrev_b32_e32 v162, 16, v221
	v_and_b32_e32 v163, 0xffff0000, v221
	v_pk_fma_f32 v[156:157], v[104:105], 0.5, v[156:157] op_sel_hi:[1,0,1]
	v_pk_fma_f32 v[158:159], v[106:107], 0.5, v[158:159] op_sel_hi:[1,0,1]
	v_pk_fma_f32 v[160:161], v[100:101], 0.5, v[160:161] op_sel_hi:[1,0,1]
	v_pk_fma_f32 v[162:163], v[102:103], 0.5, v[162:163] op_sel_hi:[1,0,1]
	v_pk_fma_f32 v[164:165], v[156:157], v[156:157], v[164:165]
	v_pk_fma_f32 v[164:165], v[158:159], v[158:159], v[164:165]
	v_pk_fma_f32 v[164:165], v[160:161], v[160:161], v[164:165]
	v_pk_fma_f32 v[164:165], v[162:163], v[162:163], v[164:165]
	v_mfma_f32_16x16x32_bf16 v[104:107], v[132:135], v[132:135], 0
	v_mfma_f32_16x16x32_bf16 v[100:103], v[132:135], v[132:135], 0
	v_cvt_pk_bf16_f32 v218, v156, v157
	v_cvt_pk_bf16_f32 v219, v158, v159
	v_cvt_pk_bf16_f32 v220, v160, v161
	v_cvt_pk_bf16_f32 v221, v162, v163
	s_add_u32 s100, s98, 0x15000
	s_addc_u32 s101, s99, 0
	global_store_dwordx4 v222, v[218:221], s[100:101] offset:2048
	v_add_f32_e32 v173, v164, v165
	ds_bpermute_b32 v156, v174, v166
	ds_bpermute_b32 v157, v174, v167
	ds_bpermute_b32 v158, v174, v168
	ds_bpermute_b32 v159, v174, v169
	ds_bpermute_b32 v160, v174, v170
	ds_bpermute_b32 v161, v174, v171
	ds_bpermute_b32 v162, v174, v172
	ds_bpermute_b32 v163, v174, v173
	s_waitcnt lgkmcnt(0)
	v_add_f32_e32 v166, v166, v156
	v_add_f32_e32 v167, v167, v157
	v_add_f32_e32 v168, v168, v158
	v_add_f32_e32 v169, v169, v159
	v_add_f32_e32 v170, v170, v160
	v_add_f32_e32 v171, v171, v161
	v_add_f32_e32 v172, v172, v162
	v_add_f32_e32 v173, v173, v163
	ds_bpermute_b32 v156, v175, v166
	ds_bpermute_b32 v157, v175, v167
	ds_bpermute_b32 v158, v175, v168
	ds_bpermute_b32 v159, v175, v169
	ds_bpermute_b32 v160, v175, v170
	ds_bpermute_b32 v161, v175, v171
	ds_bpermute_b32 v162, v175, v172
	ds_bpermute_b32 v163, v175, v173
	s_waitcnt lgkmcnt(0)
	v_add_f32_e32 v166, v166, v156
	v_add_f32_e32 v167, v167, v157
	v_add_f32_e32 v168, v168, v158
	v_add_f32_e32 v169, v169, v159
	v_add_f32_e32 v170, v170, v160
	v_add_f32_e32 v171, v171, v161
	v_add_f32_e32 v172, v172, v162
	v_add_f32_e32 v173, v173, v163
	s_mov_b64 s[34:35], exec
	s_mov_b64 exec, 0xffff
	global_store_dword v222, v166, s[22:23]
	global_store_dword v222, v167, s[22:23] offset:2048
	s_add_u32 s100, s22, 0x1000
	s_addc_u32 s101, s23, 0
	global_store_dword v222, v168, s[100:101]
	s_add_u32 s100, s22, 0x1000
	s_addc_u32 s101, s23, 0
	global_store_dword v222, v169, s[100:101] offset:2048
	s_add_u32 s100, s22, 0x4000
	s_addc_u32 s101, s23, 0
	global_store_dword v222, v170, s[100:101]
	s_add_u32 s100, s22, 0x4000
	s_addc_u32 s101, s23, 0
	global_store_dword v222, v171, s[100:101] offset:2048
	s_add_u32 s100, s22, 0x5000
	s_addc_u32 s101, s23, 0
	global_store_dword v222, v172, s[100:101]
	s_add_u32 s100, s22, 0x5000
	s_addc_u32 s101, s23, 0
	global_store_dword v222, v173, s[100:101] offset:2048
	s_mov_b64 exec, s[34:35]
	s_and_b64 vcc, exec, s[40:41]
	s_mov_b64 s[10:11], -1
	s_cbranch_vccnz .LBB0_286
	s_andn2_b64 vcc, exec, s[18:19]
	s_cbranch_vccnz .LBB0_285
	s_barrier
	s_branch .LBB0_285

; #define PG8_STAGE(bufoff, gbase, voff) do { _Pragma("unroll") for (int _i = 0; _i < 2; ++_i) \
;         __builtin_amdgcn_global_load_lds((const unsigned*)((const char*)(gbase) + (voff)[_i]), (LAS unsigned*)(lds + (bufoff) + ldsw + _i * 8192), 16, 0, 0); } while (0)
; #define PG8_LDA(dst, b, h) do { _Pragma("unroll") for (int m = 0; m < 4; ++m) _Pragma("unroll") for (int k = 0; k < 2; ++k) dst[m][k] = *(const LAS bf16x8*)(lds + PG8_SA(b, h) + aoff + m * 2048 + k * 1024); } while (0)
; #define PG8_LDB(dst, b, h) do { _Pragma("unroll") for (int n = 0; n < 2; ++n) _Pragma("unroll") for (int k = 0; k < 2; ++k) dst[n][k] = *(const LAS bf16x8*)(lds + PG8_SB(b, h) + boff + n * 2048 + k * 1024); } while (0)
; #define PG8_MMA(ai, bj, At, Bt) do { __builtin_amdgcn_s_setprio(1); _Pragma("unroll") for (int m = 0; m < 4; ++m) _Pragma("unroll") for (int n = 0; n < 2; ++n) _Pragma("unroll") for (int k = 0; k < 2; ++k) \
;         acc[ai][bj][m][n] = __builtin_amdgcn_mfma_f32_16x16x32_bf16(Bt[n][k], At[m][k], acc[ai][bj][m][n], 0, 0, 0); __builtin_amdgcn_s_setprio(0); } while (0)
; #define PG8_WAIT_V(n) asm volatile("s_waitcnt vmcnt(" #n ")" ::: "memory")
; #define PG8_WAIT_L(n) asm volatile("s_waitcnt lgkmcnt(" #n ")" ::: "memory")
; #define PG8_BAR __builtin_amdgcn_s_barrier()
; #define PG8_SCHED __builtin_amdgcn_sched_barrier(0)
; template <class Epi, bool ALIGN_EPI>
; __device__ __forceinline__ void gemm_phase(LAS unsigned char* lds, const Gemm g, const StaticOrder& S, const Epi& E, const int tid) {
;     ...
;         const char* nA = has_next ? (const char*)g.A + (size_t)nxt.pm * tstepA + (size_t)nxt.pn * g.acs : cA; const char* nB = has_next ? (const char*)g.Bt + (size_t)nxt.pn * tstepB : cB;
;         for (int t = 0; t < nt; t += 2) {
;             const bool last = (t == nt - 2);
;             const char* a1 = cA + (size_t)(t + 1) * kstepA;
;             const char* a2 = last ? nA : cA + (size_t)(t + 2) * kstepA; const char* b2 = last ? nB : cB + (size_t)(t + 2) * kstepB;
;             const char* a3 = a2 + kstepA; const char* b3 = b2 + kstepB;
;             PG8_LDB(B0, 0, 0); PG8_LDB(B1, 0, 1); PG8_SCHED; PG8_LDA(At, 0, 0); PG8_STAGE(PG8_SA(1, 1), a1 + hstepA, voffA);
;             PG8_WAIT_V(8); PG8_WAIT_L(0); PG8_BAR; PG8_MMA(0, 0, At, B0); PG8_MMA(0, 1, At, B1); PG8_BAR; PG8_SCHED;
.LBB0_847:
	s_add_u32 s22, s10, 0xfff80080
	s_addc_u32 s23, s11, -1
	s_add_i32 s87, 0, 0x10000
	s_cmp_eq_u32 s86, 28
	s_cselect_b32 s35, s49, s23
	s_cselect_b32 s34, s82, s22
	v_add_u32_e32 v0, s87, v154
	s_cselect_b32 s23, s47, s85
	s_cselect_b32 s22, s83, s84
	s_add_i32 s90, 0, 0x14000
	s_waitcnt lgkmcnt(0)
	ds_read_b128 v[132:135], v0
	ds_read_b128 v[148:151], v0 offset:1024
	ds_read_b128 v[156:159], v0 offset:2048
	ds_read_b128 v[160:163], v0 offset:3072
	v_add_u32_e32 v0, s90, v154
	ds_read_b128 v[164:167], v0
	ds_read_b128 v[168:171], v0 offset:1024
	ds_read_b128 v[172:175], v0 offset:2048
	ds_read_b128 v[176:179], v0 offset:3072
	s_add_i32 m0, s70, 0xc000
	ds_read_b128 v[180:183], v155
	ds_read_b128 v[184:187], v155 offset:1024
	ds_read_b128 v[188:191], v155 offset:2048
	ds_read_b128 v[192:195], v155 offset:3072
	ds_read_b128 v[196:199], v155 offset:4096
	ds_read_b128 v[214:217], v155 offset:5120
	ds_read_b128 v[218:221], v155 offset:6144

; #define PG8_STAGE(bufoff, gbase, voff) do { _Pragma("unroll") for (int _i = 0; _i < 2; ++_i) \
;         __builtin_amdgcn_global_load_lds((const unsigned*)((const char*)(gbase) + (voff)[_i]), (LAS unsigned*)(lds + (bufoff) + ldsw + _i * 8192), 16, 0, 0); } while (0)
; #define PG8_LDA(dst, b, h) do { _Pragma("unroll") for (int m = 0; m < 4; ++m) _Pragma("unroll") for (int k = 0; k < 2; ++k) dst[m][k] = *(const LAS bf16x8*)(lds + PG8_SA(b, h) + aoff + m * 2048 + k * 1024); } while (0)
; #define PG8_LDB(dst, b, h) do { _Pragma("unroll") for (int n = 0; n < 2; ++n) _Pragma("unroll") for (int k = 0; k < 2; ++k) dst[n][k] = *(const LAS bf16x8*)(lds + PG8_SB(b, h) + boff + n * 2048 + k * 1024); } while (0)
; #define PG8_MMA(ai, bj, At, Bt) do { __builtin_amdgcn_s_setprio(1); _Pragma("unroll") for (int m = 0; m < 4; ++m) _Pragma("unroll") for (int n = 0; n < 2; ++n) _Pragma("unroll") for (int k = 0; k < 2; ++k) \
;         acc[ai][bj][m][n] = __builtin_amdgcn_mfma_f32_16x16x32_bf16(Bt[n][k], At[m][k], acc[ai][bj][m][n], 0, 0, 0); __builtin_amdgcn_s_setprio(0); } while (0)
; #define PG8_WAIT_V(n) asm volatile("s_waitcnt vmcnt(" #n ")" ::: "memory")
; #define PG8_WAIT_L(n) asm volatile("s_waitcnt lgkmcnt(" #n ")" ::: "memory")
; #define PG8_BAR __builtin_amdgcn_s_barrier()
; #define PG8_SCHED __builtin_amdgcn_sched_barrier(0)
; template <class Epi, bool ALIGN_EPI>
; __device__ __forceinline__ void gemm_phase(LAS unsigned char* lds, const Gemm g, const StaticOrder& S, const Epi& E, const int tid) {
;     ...
;             PG8_LDB(B0, 0, 0); PG8_LDB(B1, 0, 1); PG8_SCHED; PG8_LDA(At, 0, 0); PG8_STAGE(PG8_SA(1, 1), a1 + hstepA, voffA);
;             PG8_WAIT_V(8); PG8_WAIT_L(0); PG8_BAR; PG8_MMA(0, 0, At, B0); PG8_MMA(0, 1, At, B1); PG8_BAR; PG8_SCHED;
	global_load_lds_dwordx4 v144, s[10:11]
	s_add_i32 m0, s70, 0xe000
	ds_read_b128 v[222:225], v155 offset:7168
	global_load_lds_dwordx4 v146, s[10:11]
	s_waitcnt vmcnt(8)
	s_waitcnt lgkmcnt(0)
	s_barrier


; #define PG8_MMA(ai, bj, At, Bt) do { __builtin_amdgcn_s_setprio(1); _Pragma("unroll") for (int m = 0; m < 4; ++m) _Pragma("unroll") for (int n = 0; n < 2; ++n) _Pragma("unroll") for (int k = 0; k < 2; ++k) \
;         acc[ai][bj][m][n] = __builtin_amdgcn_mfma_f32_16x16x32_bf16(Bt[n][k], At[m][k], acc[ai][bj][m][n], 0, 0, 0); __builtin_amdgcn_s_setprio(0); } while (0)
; #define PG8_WAIT_V(n) asm volatile("s_waitcnt vmcnt(" #n ")" ::: "memory")
; #define PG8_WAIT_L(n) asm volatile("s_waitcnt lgkmcnt(" #n ")" ::: "memory")
; #define PG8_BAR __builtin_amdgcn_s_barrier()
; #define PG8_SCHED __builtin_amdgcn_sched_barrier(0)
; template <class Epi, bool ALIGN_EPI>
; __device__ __forceinline__ void gemm_phase(LAS unsigned char* lds, const Gemm g, const StaticOrder& S, const Epi& E, const int tid) {
;     ...
;             PG8_WAIT_V(8); PG8_WAIT_L(0); PG8_BAR; PG8_MMA(0, 0, At, B0); PG8_MMA(0, 1, At, B1); PG8_BAR; PG8_SCHED;
	v_mfma_f32_16x16x32_bf16 v[8:11], v[132:135], v[180:183], v[8:11]
	v_mfma_f32_16x16x32_bf16 v[56:59], v[156:159], v[180:183], v[56:59]
	v_mfma_f32_16x16x32_bf16 v[52:55], v[132:135], v[188:191], v[52:55]
	v_mfma_f32_16x16x32_bf16 v[48:51], v[156:159], v[188:191], v[48:51]
	v_mfma_f32_16x16x32_bf16 v[44:47], v[132:135], v[196:199], v[44:47]
	v_mfma_f32_16x16x32_bf16 v[40:43], v[156:159], v[196:199], v[40:43]
	v_mfma_f32_16x16x32_bf16 v[36:39], v[132:135], v[218:221], v[36:39]
	v_mfma_f32_16x16x32_bf16 v[32:35], v[156:159], v[218:221], v[32:35]
	v_mfma_f32_16x16x32_bf16 v[8:11], v[148:151], v[184:187], v[8:11]
	v_mfma_f32_16x16x32_bf16 v[56:59], v[160:163], v[184:187], v[56:59]
	v_mfma_f32_16x16x32_bf16 v[52:55], v[148:151], v[192:195], v[52:55]
	v_mfma_f32_16x16x32_bf16 v[48:51], v[160:163], v[192:195], v[48:51]
	v_mfma_f32_16x16x32_bf16 v[44:47], v[148:151], v[214:217], v[44:47]
	v_mfma_f32_16x16x32_bf16 v[40:43], v[160:163], v[214:217], v[40:43]
	v_mfma_f32_16x16x32_bf16 v[36:39], v[148:151], v[222:225], v[36:39]
	v_mfma_f32_16x16x32_bf16 v[32:35], v[160:163], v[222:225], v[32:35]


; #define PG8_MMA(ai, bj, At, Bt) do { __builtin_amdgcn_s_setprio(1); _Pragma("unroll") for (int m = 0; m < 4; ++m) _Pragma("unroll") for (int n = 0; n < 2; ++n) _Pragma("unroll") for (int k = 0; k < 2; ++k) \
;         acc[ai][bj][m][n] = __builtin_amdgcn_mfma_f32_16x16x32_bf16(Bt[n][k], At[m][k], acc[ai][bj][m][n], 0, 0, 0); __builtin_amdgcn_s_setprio(0); } while (0)
; #define PG8_WAIT_V(n) asm volatile("s_waitcnt vmcnt(" #n ")" ::: "memory")
; #define PG8_WAIT_L(n) asm volatile("s_waitcnt lgkmcnt(" #n ")" ::: "memory")
; #define PG8_BAR __builtin_amdgcn_s_barrier()
; #define PG8_SCHED __builtin_amdgcn_sched_barrier(0)
; template <class Epi, bool ALIGN_EPI>
; __device__ __forceinline__ void gemm_phase(LAS unsigned char* lds, const Gemm g, const StaticOrder& S, const Epi& E, const int tid) {
;     ...
;             PG8_WAIT_V(8); PG8_WAIT_L(0); PG8_BAR; PG8_MMA(0, 0, At, B0); PG8_MMA(0, 1, At, B1); PG8_BAR; PG8_SCHED;
	v_mfma_f32_16x16x32_bf16 v[2:5], v[164:167], v[180:183], v[4:7]
	v_mfma_f32_16x16x32_bf16 v[28:31], v[172:175], v[180:183], v[28:31]
	v_mfma_f32_16x16x32_bf16 v[96:99], v[164:167], v[188:191], v[96:99]
	v_mfma_f32_16x16x32_bf16 v[92:95], v[172:175], v[188:191], v[92:95]
	v_mfma_f32_16x16x32_bf16 v[88:91], v[164:167], v[196:199], v[88:91]
	v_mfma_f32_16x16x32_bf16 v[84:87], v[172:175], v[196:199], v[84:87]
	v_mfma_f32_16x16x32_bf16 v[80:83], v[164:167], v[218:221], v[80:83]
	v_mfma_f32_16x16x32_bf16 v[76:79], v[172:175], v[218:221], v[76:79]
	v_mfma_f32_16x16x32_bf16 v[2:5], v[168:171], v[184:187], v[2:5]
	v_mfma_f32_16x16x32_bf16 v[28:31], v[176:179], v[184:187], v[28:31]
	v_mfma_f32_16x16x32_bf16 v[96:99], v[168:171], v[192:195], v[96:99]
	v_mfma_f32_16x16x32_bf16 v[92:95], v[176:179], v[192:195], v[92:95]
	v_mfma_f32_16x16x32_bf16 v[88:91], v[168:171], v[214:217], v[88:91]
	v_mfma_f32_16x16x32_bf16 v[84:87], v[176:179], v[214:217], v[84:87]
	v_mfma_f32_16x16x32_bf16 v[80:83], v[168:171], v[222:225], v[80:83]
	v_mfma_f32_16x16x32_bf16 v[76:79], v[176:179], v[222:225], v[76:79]

; #define PG8_STAGE(bufoff, gbase, voff) do { _Pragma("unroll") for (int _i = 0; _i < 2; ++_i) \
;         __builtin_amdgcn_global_load_lds((const unsigned*)((const char*)(gbase) + (voff)[_i]), (LAS unsigned*)(lds + (bufoff) + ldsw + _i * 8192), 16, 0, 0); } while (0)
; #define PG8_LDA(dst, b, h) do { _Pragma("unroll") for (int m = 0; m < 4; ++m) _Pragma("unroll") for (int k = 0; k < 2; ++k) dst[m][k] = *(const LAS bf16x8*)(lds + PG8_SA(b, h) + aoff + m * 2048 + k * 1024); } while (0)
; template <class Epi, bool ALIGN_EPI>
; __device__ __forceinline__ void gemm_phase(LAS unsigned char* lds, const Gemm g, const StaticOrder& S, const Epi& E, const int tid) {
;     ...
;             PG8_LDA(At, 0, 1); PG8_STAGE(PG8_SB(0, 0), b2, voffB); PG8_STAGE(PG8_SB(0, 1), b2 + hstepB, voffB); PG8_STAGE(PG8_SA(0, 0), a2, voffA);
	s_barrier
	s_add_i32 s87, s87, s61
	s_mov_b32 m0, s87
	ds_read_b128 v[180:183], v155 offset:16384
	ds_read_b128 v[184:187], v155 offset:17408
	ds_read_b128 v[188:191], v155 offset:18432
	ds_read_b128 v[192:195], v155 offset:19456
	ds_read_b128 v[196:199], v155 offset:20480
	ds_read_b128 v[214:217], v155 offset:21504


; #define PG8_STAGE(bufoff, gbase, voff) do { _Pragma("unroll") for (int _i = 0; _i < 2; ++_i) \
;         __builtin_amdgcn_global_load_lds((const unsigned*)((const char*)(gbase) + (voff)[_i]), (LAS unsigned*)(lds + (bufoff) + ldsw + _i * 8192), 16, 0, 0); } while (0)
; #define PG8_LDA(dst, b, h) do { _Pragma("unroll") for (int m = 0; m < 4; ++m) _Pragma("unroll") for (int k = 0; k < 2; ++k) dst[m][k] = *(const LAS bf16x8*)(lds + PG8_SA(b, h) + aoff + m * 2048 + k * 1024); } while (0)
; #define PG8_MMA(ai, bj, At, Bt) do { __builtin_amdgcn_s_setprio(1); _Pragma("unroll") for (int m = 0; m < 4; ++m) _Pragma("unroll") for (int n = 0; n < 2; ++n) _Pragma("unroll") for (int k = 0; k < 2; ++k) \
;         acc[ai][bj][m][n] = __builtin_amdgcn_mfma_f32_16x16x32_bf16(Bt[n][k], At[m][k], acc[ai][bj][m][n], 0, 0, 0); __builtin_amdgcn_s_setprio(0); } while (0)
; #define PG8_WAIT_V(n) asm volatile("s_waitcnt vmcnt(" #n ")" ::: "memory")
; #define PG8_WAIT_L(n) asm volatile("s_waitcnt lgkmcnt(" #n ")" ::: "memory")
; #define PG8_BAR __builtin_amdgcn_s_barrier()
; #define PG8_SCHED __builtin_amdgcn_sched_barrier(0)
; template <class Epi, bool ALIGN_EPI>
; __device__ __forceinline__ void gemm_phase(LAS unsigned char* lds, const Gemm g, const StaticOrder& S, const Epi& E, const int tid) {
;     ...
;             PG8_LDA(At, 0, 1); PG8_STAGE(PG8_SB(0, 0), b2, voffB); PG8_STAGE(PG8_SB(0, 1), b2 + hstepB, voffB); PG8_STAGE(PG8_SA(0, 0), a2, voffA);
;             PG8_WAIT_V(8); PG8_WAIT_L(0); PG8_BAR; PG8_MMA(1, 0, At, B0); PG8_MMA(1, 1, At, B1); PG8_BAR; PG8_SCHED;
	global_load_lds_dwordx4 v140, s[22:23]
	s_add_i32 m0, s87, 0x2000
	s_add_u32 s88, s22, 0x4000
	s_addc_u32 s89, s23, 0
	s_add_i32 s87, s90, s61
	global_load_lds_dwordx4 v136, s[22:23]
	s_mov_b32 m0, s87
	v_lshl_add_u64 v[152:153], s[34:35], 0, v[142:143]
	global_load_lds_dwordx4 v140, s[88:89]
	s_add_i32 m0, s87, 0x2000
	v_lshl_add_u64 v[200:201], s[34:35], 0, v[138:139]
	global_load_lds_dwordx4 v136, s[88:89]
	s_mov_b32 m0, s70
	ds_read_b128 v[222:225], v155 offset:23552
	global_load_lds_dwordx4 v[152:153], off
	s_mov_b32 m0, s71
	ds_read_b128 v[218:221], v155 offset:22528
	global_load_lds_dwordx4 v[200:201], off
	s_waitcnt vmcnt(8)
	s_waitcnt lgkmcnt(0)
	s_barrier


; #define PG8_MMA(ai, bj, At, Bt) do { __builtin_amdgcn_s_setprio(1); _Pragma("unroll") for (int m = 0; m < 4; ++m) _Pragma("unroll") for (int n = 0; n < 2; ++n) _Pragma("unroll") for (int k = 0; k < 2; ++k) \
;         acc[ai][bj][m][n] = __builtin_amdgcn_mfma_f32_16x16x32_bf16(Bt[n][k], At[m][k], acc[ai][bj][m][n], 0, 0, 0); __builtin_amdgcn_s_setprio(0); } while (0)
; #define PG8_WAIT_V(n) asm volatile("s_waitcnt vmcnt(" #n ")" ::: "memory")
; #define PG8_WAIT_L(n) asm volatile("s_waitcnt lgkmcnt(" #n ")" ::: "memory")
; #define PG8_BAR __builtin_amdgcn_s_barrier()
; #define PG8_SCHED __builtin_amdgcn_sched_barrier(0)
; template <class Epi, bool ALIGN_EPI>
; __device__ __forceinline__ void gemm_phase(LAS unsigned char* lds, const Gemm g, const StaticOrder& S, const Epi& E, const int tid) {
;     ...
;             PG8_WAIT_V(8); PG8_WAIT_L(0); PG8_BAR; PG8_MMA(1, 0, At, B0); PG8_MMA(1, 1, At, B1); PG8_BAR; PG8_SCHED;
	v_mfma_f32_16x16x32_bf16 v[24:27], v[132:135], v[180:183], v[24:27]
	v_mfma_f32_16x16x32_bf16 v[20:23], v[156:159], v[180:183], v[20:23]
	v_mfma_f32_16x16x32_bf16 v[64:67], v[132:135], v[188:191], v[64:67]
	v_mfma_f32_16x16x32_bf16 v[72:75], v[156:159], v[188:191], v[72:75]
	v_mfma_f32_16x16x32_bf16 v[16:19], v[132:135], v[196:199], v[16:19]
	v_mfma_f32_16x16x32_bf16 v[12:15], v[156:159], v[196:199], v[12:15]
	v_mfma_f32_16x16x32_bf16 v[60:63], v[132:135], v[218:221], v[60:63]
	v_mfma_f32_16x16x32_bf16 v[68:71], v[156:159], v[218:221], v[68:71]
	v_mfma_f32_16x16x32_bf16 v[24:27], v[148:151], v[184:187], v[24:27]
	v_mfma_f32_16x16x32_bf16 v[20:23], v[160:163], v[184:187], v[20:23]
	v_mfma_f32_16x16x32_bf16 v[64:67], v[148:151], v[192:195], v[64:67]
	v_mfma_f32_16x16x32_bf16 v[72:75], v[160:163], v[192:195], v[72:75]
	v_mfma_f32_16x16x32_bf16 v[16:19], v[148:151], v[214:217], v[16:19]
	v_mfma_f32_16x16x32_bf16 v[12:15], v[160:163], v[214:217], v[12:15]
	v_mfma_f32_16x16x32_bf16 v[60:63], v[148:151], v[222:225], v[60:63]
	v_mfma_f32_16x16x32_bf16 v[68:71], v[160:163], v[222:225], v[68:71]


; #define PG8_MMA(ai, bj, At, Bt) do { __builtin_amdgcn_s_setprio(1); _Pragma("unroll") for (int m = 0; m < 4; ++m) _Pragma("unroll") for (int n = 0; n < 2; ++n) _Pragma("unroll") for (int k = 0; k < 2; ++k) \
;         acc[ai][bj][m][n] = __builtin_amdgcn_mfma_f32_16x16x32_bf16(Bt[n][k], At[m][k], acc[ai][bj][m][n], 0, 0, 0); __builtin_amdgcn_s_setprio(0); } while (0)
; #define PG8_WAIT_V(n) asm volatile("s_waitcnt vmcnt(" #n ")" ::: "memory")
; #define PG8_WAIT_L(n) asm volatile("s_waitcnt lgkmcnt(" #n ")" ::: "memory")
; #define PG8_BAR __builtin_amdgcn_s_barrier()
; #define PG8_SCHED __builtin_amdgcn_sched_barrier(0)
; template <class Epi, bool ALIGN_EPI>
; __device__ __forceinline__ void gemm_phase(LAS unsigned char* lds, const Gemm g, const StaticOrder& S, const Epi& E, const int tid) {
;     ...
;             PG8_WAIT_V(8); PG8_WAIT_L(0); PG8_BAR; PG8_MMA(1, 0, At, B0); PG8_MMA(1, 1, At, B1); PG8_BAR; PG8_SCHED;
	v_mfma_f32_16x16x32_bf16 v[128:131], v[164:167], v[180:183], v[128:131]
	v_mfma_f32_16x16x32_bf16 v[124:127], v[172:175], v[180:183], v[124:127]
	v_mfma_f32_16x16x32_bf16 v[120:123], v[164:167], v[188:191], v[120:123]
	v_mfma_f32_16x16x32_bf16 v[116:119], v[172:175], v[188:191], v[116:119]
	v_mfma_f32_16x16x32_bf16 v[112:115], v[164:167], v[196:199], v[112:115]
	v_mfma_f32_16x16x32_bf16 v[108:111], v[172:175], v[196:199], v[108:111]
	v_mfma_f32_16x16x32_bf16 v[104:107], v[164:167], v[218:221], v[104:107]
	v_mfma_f32_16x16x32_bf16 v[100:103], v[172:175], v[218:221], v[100:103]
	v_mfma_f32_16x16x32_bf16 v[128:131], v[168:171], v[184:187], v[128:131]
	v_mfma_f32_16x16x32_bf16 v[124:127], v[176:179], v[184:187], v[124:127]
	v_mfma_f32_16x16x32_bf16 v[120:123], v[168:171], v[192:195], v[120:123]
	v_mfma_f32_16x16x32_bf16 v[116:119], v[176:179], v[192:195], v[116:119]
	v_mfma_f32_16x16x32_bf16 v[112:115], v[168:171], v[214:217], v[112:115]
	v_mfma_f32_16x16x32_bf16 v[108:111], v[176:179], v[214:217], v[108:111]
	v_mfma_f32_16x16x32_bf16 v[104:107], v[168:171], v[222:225], v[104:107]
	v_mfma_f32_16x16x32_bf16 v[100:103], v[176:179], v[222:225], v[100:103]

; #define PG8_STAGE(bufoff, gbase, voff) do { _Pragma("unroll") for (int _i = 0; _i < 2; ++_i) \
;         __builtin_amdgcn_global_load_lds((const unsigned*)((const char*)(gbase) + (voff)[_i]), (LAS unsigned*)(lds + (bufoff) + ldsw + _i * 8192), 16, 0, 0); } while (0)
; #define PG8_LDA(dst, b, h) do { _Pragma("unroll") for (int m = 0; m < 4; ++m) _Pragma("unroll") for (int k = 0; k < 2; ++k) dst[m][k] = *(const LAS bf16x8*)(lds + PG8_SA(b, h) + aoff + m * 2048 + k * 1024); } while (0)
; #define PG8_LDB(dst, b, h) do { _Pragma("unroll") for (int n = 0; n < 2; ++n) _Pragma("unroll") for (int k = 0; k < 2; ++k) dst[n][k] = *(const LAS bf16x8*)(lds + PG8_SB(b, h) + boff + n * 2048 + k * 1024); } while (0)
; #define PG8_SCHED __builtin_amdgcn_sched_barrier(0)
; template <class Epi, bool ALIGN_EPI>
; __device__ __forceinline__ void gemm_phase(LAS unsigned char* lds, const Gemm g, const StaticOrder& S, const Epi& E, const int tid) {
;     ...
;             PG8_LDB(B0, 1, 0); PG8_LDB(B1, 1, 1); PG8_SCHED; PG8_LDA(At, 1, 0); PG8_STAGE(PG8_SA(0, 1), a2 + hstepA, voffA);
	s_barrier
	s_add_i32 s87, 0, 0x18000
	v_add_u32_e32 v0, s87, v154
	s_add_i32 s88, 0, 0x1c000
	ds_read_b128 v[132:135], v0
	ds_read_b128 v[148:151], v0 offset:1024
	ds_read_b128 v[156:159], v0 offset:2048
	ds_read_b128 v[160:163], v0 offset:3072
	v_add_u32_e32 v0, s88, v154
	ds_read_b128 v[164:167], v0
	ds_read_b128 v[168:171], v0 offset:1024
	ds_read_b128 v[172:175], v0 offset:2048
	ds_read_b128 v[176:179], v0 offset:3072
	s_add_u32 s34, s34, 0x80000
	s_addc_u32 s35, s35, 0
	s_mov_b32 m0, s72
	ds_read_b128 v[180:183], v155 offset:32768
	ds_read_b128 v[184:187], v155 offset:33792
	ds_read_b128 v[188:191], v155 offset:34816
	ds_read_b128 v[192:195], v155 offset:35840
	ds_read_b128 v[196:199], v155 offset:36864
	ds_read_b128 v[214:217], v155 offset:37888
	ds_read_b128 v[218:221], v155 offset:38912

; #define PG8_STAGE(bufoff, gbase, voff) do { _Pragma("unroll") for (int _i = 0; _i < 2; ++_i) \
;         __builtin_amdgcn_global_load_lds((const unsigned*)((const char*)(gbase) + (voff)[_i]), (LAS unsigned*)(lds + (bufoff) + ldsw + _i * 8192), 16, 0, 0); } while (0)
; #define PG8_LDA(dst, b, h) do { _Pragma("unroll") for (int m = 0; m < 4; ++m) _Pragma("unroll") for (int k = 0; k < 2; ++k) dst[m][k] = *(const LAS bf16x8*)(lds + PG8_SA(b, h) + aoff + m * 2048 + k * 1024); } while (0)
; #define PG8_LDB(dst, b, h) do { _Pragma("unroll") for (int n = 0; n < 2; ++n) _Pragma("unroll") for (int k = 0; k < 2; ++k) dst[n][k] = *(const LAS bf16x8*)(lds + PG8_SB(b, h) + boff + n * 2048 + k * 1024); } while (0)
; #define PG8_MMA(ai, bj, At, Bt) do { __builtin_amdgcn_s_setprio(1); _Pragma("unroll") for (int m = 0; m < 4; ++m) _Pragma("unroll") for (int n = 0; n < 2; ++n) _Pragma("unroll") for (int k = 0; k < 2; ++k) \
;         acc[ai][bj][m][n] = __builtin_amdgcn_mfma_f32_16x16x32_bf16(Bt[n][k], At[m][k], acc[ai][bj][m][n], 0, 0, 0); __builtin_amdgcn_s_setprio(0); } while (0)
; #define PG8_WAIT_V(n) asm volatile("s_waitcnt vmcnt(" #n ")" ::: "memory")
; #define PG8_WAIT_L(n) asm volatile("s_waitcnt lgkmcnt(" #n ")" ::: "memory")
; #define PG8_BAR __builtin_amdgcn_s_barrier()
; #define PG8_SCHED __builtin_amdgcn_sched_barrier(0)
; template <class Epi, bool ALIGN_EPI>
; __device__ __forceinline__ void gemm_phase(LAS unsigned char* lds, const Gemm g, const StaticOrder& S, const Epi& E, const int tid) {
;     ...
;             PG8_LDB(B0, 1, 0); PG8_LDB(B1, 1, 1); PG8_SCHED; PG8_LDA(At, 1, 0); PG8_STAGE(PG8_SA(0, 1), a2 + hstepA, voffA);
;             PG8_WAIT_V(8); PG8_WAIT_L(0); PG8_BAR; PG8_MMA(0, 0, At, B0); PG8_MMA(0, 1, At, B1); PG8_BAR; PG8_SCHED;
	global_load_lds_dwordx4 v142, s[34:35]
	s_mov_b32 m0, s73
	ds_read_b128 v[222:225], v155 offset:39936
	global_load_lds_dwordx4 v138, s[34:35]
	s_waitcnt vmcnt(8)
	s_waitcnt lgkmcnt(0)
	s_barrier


; #define PG8_MMA(ai, bj, At, Bt) do { __builtin_amdgcn_s_setprio(1); _Pragma("unroll") for (int m = 0; m < 4; ++m) _Pragma("unroll") for (int n = 0; n < 2; ++n) _Pragma("unroll") for (int k = 0; k < 2; ++k) \
;         acc[ai][bj][m][n] = __builtin_amdgcn_mfma_f32_16x16x32_bf16(Bt[n][k], At[m][k], acc[ai][bj][m][n], 0, 0, 0); __builtin_amdgcn_s_setprio(0); } while (0)
; #define PG8_WAIT_V(n) asm volatile("s_waitcnt vmcnt(" #n ")" ::: "memory")
; #define PG8_WAIT_L(n) asm volatile("s_waitcnt lgkmcnt(" #n ")" ::: "memory")
; #define PG8_BAR __builtin_amdgcn_s_barrier()
; #define PG8_SCHED __builtin_amdgcn_sched_barrier(0)
; template <class Epi, bool ALIGN_EPI>
; __device__ __forceinline__ void gemm_phase(LAS unsigned char* lds, const Gemm g, const StaticOrder& S, const Epi& E, const int tid) {
;     ...
;             PG8_WAIT_V(8); PG8_WAIT_L(0); PG8_BAR; PG8_MMA(0, 0, At, B0); PG8_MMA(0, 1, At, B1); PG8_BAR; PG8_SCHED;
	v_mfma_f32_16x16x32_bf16 v[6:9], v[132:135], v[180:183], v[8:11]
	v_mfma_f32_16x16x32_bf16 v[56:59], v[156:159], v[180:183], v[56:59]
	v_mfma_f32_16x16x32_bf16 v[52:55], v[132:135], v[188:191], v[52:55]
	v_mfma_f32_16x16x32_bf16 v[48:51], v[156:159], v[188:191], v[48:51]
	v_mfma_f32_16x16x32_bf16 v[44:47], v[132:135], v[196:199], v[44:47]
	v_mfma_f32_16x16x32_bf16 v[40:43], v[156:159], v[196:199], v[40:43]
	v_mfma_f32_16x16x32_bf16 v[36:39], v[132:135], v[218:221], v[36:39]
	v_mfma_f32_16x16x32_bf16 v[32:35], v[156:159], v[218:221], v[32:35]
	v_mfma_f32_16x16x32_bf16 v[8:11], v[148:151], v[184:187], v[6:9]
	v_mfma_f32_16x16x32_bf16 v[56:59], v[160:163], v[184:187], v[56:59]
	v_mfma_f32_16x16x32_bf16 v[52:55], v[148:151], v[192:195], v[52:55]
	v_mfma_f32_16x16x32_bf16 v[48:51], v[160:163], v[192:195], v[48:51]
	v_mfma_f32_16x16x32_bf16 v[44:47], v[148:151], v[214:217], v[44:47]
	v_mfma_f32_16x16x32_bf16 v[40:43], v[160:163], v[214:217], v[40:43]
	v_mfma_f32_16x16x32_bf16 v[36:39], v[148:151], v[222:225], v[36:39]
	v_mfma_f32_16x16x32_bf16 v[32:35], v[160:163], v[222:225], v[32:35]


; #define PG8_MMA(ai, bj, At, Bt) do { __builtin_amdgcn_s_setprio(1); _Pragma("unroll") for (int m = 0; m < 4; ++m) _Pragma("unroll") for (int n = 0; n < 2; ++n) _Pragma("unroll") for (int k = 0; k < 2; ++k) \
;         acc[ai][bj][m][n] = __builtin_amdgcn_mfma_f32_16x16x32_bf16(Bt[n][k], At[m][k], acc[ai][bj][m][n], 0, 0, 0); __builtin_amdgcn_s_setprio(0); } while (0)
; #define PG8_WAIT_V(n) asm volatile("s_waitcnt vmcnt(" #n ")" ::: "memory")
; #define PG8_WAIT_L(n) asm volatile("s_waitcnt lgkmcnt(" #n ")" ::: "memory")
; #define PG8_BAR __builtin_amdgcn_s_barrier()
; #define PG8_SCHED __builtin_amdgcn_sched_barrier(0)
; template <class Epi, bool ALIGN_EPI>
; __device__ __forceinline__ void gemm_phase(LAS unsigned char* lds, const Gemm g, const StaticOrder& S, const Epi& E, const int tid) {
;     ...
;             PG8_WAIT_V(8); PG8_WAIT_L(0); PG8_BAR; PG8_MMA(0, 0, At, B0); PG8_MMA(0, 1, At, B1); PG8_BAR; PG8_SCHED;
	v_mfma_f32_16x16x32_bf16 v[2:5], v[164:167], v[180:183], v[2:5]
	v_mfma_f32_16x16x32_bf16 v[28:31], v[172:175], v[180:183], v[28:31]
	v_mfma_f32_16x16x32_bf16 v[96:99], v[164:167], v[188:191], v[96:99]
	v_mfma_f32_16x16x32_bf16 v[92:95], v[172:175], v[188:191], v[92:95]
	v_mfma_f32_16x16x32_bf16 v[88:91], v[164:167], v[196:199], v[88:91]
	v_mfma_f32_16x16x32_bf16 v[84:87], v[172:175], v[196:199], v[84:87]
	v_mfma_f32_16x16x32_bf16 v[80:83], v[164:167], v[218:221], v[80:83]
	v_mfma_f32_16x16x32_bf16 v[76:79], v[172:175], v[218:221], v[76:79]
	v_mfma_f32_16x16x32_bf16 v[4:7], v[168:171], v[184:187], v[2:5]
	v_mfma_f32_16x16x32_bf16 v[28:31], v[176:179], v[184:187], v[28:31]
	v_mfma_f32_16x16x32_bf16 v[96:99], v[168:171], v[192:195], v[96:99]
	v_mfma_f32_16x16x32_bf16 v[92:95], v[176:179], v[192:195], v[92:95]
	v_mfma_f32_16x16x32_bf16 v[88:91], v[168:171], v[214:217], v[88:91]
	v_mfma_f32_16x16x32_bf16 v[84:87], v[176:179], v[214:217], v[84:87]
	v_mfma_f32_16x16x32_bf16 v[80:83], v[168:171], v[222:225], v[80:83]
	v_mfma_f32_16x16x32_bf16 v[76:79], v[176:179], v[222:225], v[76:79]

; #define PG8_STAGE(bufoff, gbase, voff) do { _Pragma("unroll") for (int _i = 0; _i < 2; ++_i) \
;         __builtin_amdgcn_global_load_lds((const unsigned*)((const char*)(gbase) + (voff)[_i]), (LAS unsigned*)(lds + (bufoff) + ldsw + _i * 8192), 16, 0, 0); } while (0)
; #define PG8_LDA(dst, b, h) do { _Pragma("unroll") for (int m = 0; m < 4; ++m) _Pragma("unroll") for (int k = 0; k < 2; ++k) dst[m][k] = *(const LAS bf16x8*)(lds + PG8_SA(b, h) + aoff + m * 2048 + k * 1024); } while (0)
; template <class Epi, bool ALIGN_EPI>
; __device__ __forceinline__ void gemm_phase(LAS unsigned char* lds, const Gemm g, const StaticOrder& S, const Epi& E, const int tid) {
;     ...
;             PG8_LDA(At, 1, 1); PG8_STAGE(PG8_SB(1, 0), b3, voffB); PG8_STAGE(PG8_SB(1, 1), b3 + hstepB, voffB); PG8_STAGE(PG8_SA(1, 0), a3, voffA);
	s_barrier
	s_add_u32 s34, s22, 0x8000
	s_addc_u32 s35, s23, 0
	s_add_i32 s87, s87, s61
	s_mov_b32 m0, s87
	ds_read_b128 v[180:183], v155 offset:49152
	ds_read_b128 v[184:187], v155 offset:50176
	ds_read_b128 v[188:191], v155 offset:51200
	ds_read_b128 v[192:195], v155 offset:52224


; #define PG8_STAGE(bufoff, gbase, voff) do { _Pragma("unroll") for (int _i = 0; _i < 2; ++_i) \
;         __builtin_amdgcn_global_load_lds((const unsigned*)((const char*)(gbase) + (voff)[_i]), (LAS unsigned*)(lds + (bufoff) + ldsw + _i * 8192), 16, 0, 0); } while (0)
; #define PG8_LDA(dst, b, h) do { _Pragma("unroll") for (int m = 0; m < 4; ++m) _Pragma("unroll") for (int k = 0; k < 2; ++k) dst[m][k] = *(const LAS bf16x8*)(lds + PG8_SA(b, h) + aoff + m * 2048 + k * 1024); } while (0)
; #define PG8_MMA(ai, bj, At, Bt) do { __builtin_amdgcn_s_setprio(1); _Pragma("unroll") for (int m = 0; m < 4; ++m) _Pragma("unroll") for (int n = 0; n < 2; ++n) _Pragma("unroll") for (int k = 0; k < 2; ++k) \
;         acc[ai][bj][m][n] = __builtin_amdgcn_mfma_f32_16x16x32_bf16(Bt[n][k], At[m][k], acc[ai][bj][m][n], 0, 0, 0); __builtin_amdgcn_s_setprio(0); } while (0)
; #define PG8_WAIT_V(n) asm volatile("s_waitcnt vmcnt(" #n ")" ::: "memory")
; #define PG8_WAIT_L(n) asm volatile("s_waitcnt lgkmcnt(" #n ")" ::: "memory")
; #define PG8_BAR __builtin_amdgcn_s_barrier()
; #define PG8_SCHED __builtin_amdgcn_sched_barrier(0)
; template <class Epi, bool ALIGN_EPI>
; __device__ __forceinline__ void gemm_phase(LAS unsigned char* lds, const Gemm g, const StaticOrder& S, const Epi& E, const int tid) {
;     ...
;             PG8_LDA(At, 1, 1); PG8_STAGE(PG8_SB(1, 0), b3, voffB); PG8_STAGE(PG8_SB(1, 1), b3 + hstepB, voffB); PG8_STAGE(PG8_SA(1, 0), a3, voffA);
;             PG8_WAIT_V(8); PG8_WAIT_L(0); PG8_BAR; PG8_MMA(1, 0, At, B0); PG8_MMA(1, 1, At, B1); PG8_BAR; PG8_SCHED;
	global_load_lds_dwordx4 v140, s[34:35]
	s_add_i32 m0, s87, 0x2000
	s_add_u32 s22, s22, 0xc000
	s_addc_u32 s23, s23, 0
	global_load_lds_dwordx4 v136, s[34:35]
	s_add_i32 s34, s88, s61
	s_mov_b32 m0, s34
	ds_read_b128 v[222:225], v155 offset:56320
	global_load_lds_dwordx4 v140, s[22:23]
	s_add_i32 m0, s34, 0x2000
	ds_read_b128 v[218:221], v155 offset:55296
	global_load_lds_dwordx4 v136, s[22:23]
	v_lshl_add_u64 v[2:3], v[152:153], 0, s[6:7]
	s_mov_b32 m0, s78
	ds_read_b128 v[214:217], v155 offset:54272
	global_load_lds_dwordx4 v[2:3], off
	v_lshl_add_u64 v[2:3], v[200:201], 0, s[6:7]
	s_mov_b32 m0, s79
	ds_read_b128 v[196:199], v155 offset:53248
	global_load_lds_dwordx4 v[2:3], off
	s_waitcnt vmcnt(8)
	s_waitcnt lgkmcnt(0)
	s_barrier


; #define PG8_MMA(ai, bj, At, Bt) do { __builtin_amdgcn_s_setprio(1); _Pragma("unroll") for (int m = 0; m < 4; ++m) _Pragma("unroll") for (int n = 0; n < 2; ++n) _Pragma("unroll") for (int k = 0; k < 2; ++k) \
;         acc[ai][bj][m][n] = __builtin_amdgcn_mfma_f32_16x16x32_bf16(Bt[n][k], At[m][k], acc[ai][bj][m][n], 0, 0, 0); __builtin_amdgcn_s_setprio(0); } while (0)
; #define PG8_WAIT_V(n) asm volatile("s_waitcnt vmcnt(" #n ")" ::: "memory")
; #define PG8_WAIT_L(n) asm volatile("s_waitcnt lgkmcnt(" #n ")" ::: "memory")
; #define PG8_BAR __builtin_amdgcn_s_barrier()
; #define PG8_SCHED __builtin_amdgcn_sched_barrier(0)
; template <class Epi, bool ALIGN_EPI>
; __device__ __forceinline__ void gemm_phase(LAS unsigned char* lds, const Gemm g, const StaticOrder& S, const Epi& E, const int tid) {
;     ...
;             PG8_WAIT_V(8); PG8_WAIT_L(0); PG8_BAR; PG8_MMA(1, 0, At, B0); PG8_MMA(1, 1, At, B1); PG8_BAR; PG8_SCHED;
	v_mfma_f32_16x16x32_bf16 v[24:27], v[132:135], v[180:183], v[24:27]
	v_mfma_f32_16x16x32_bf16 v[20:23], v[156:159], v[180:183], v[20:23]
	v_mfma_f32_16x16x32_bf16 v[64:67], v[132:135], v[188:191], v[64:67]
	v_mfma_f32_16x16x32_bf16 v[72:75], v[156:159], v[188:191], v[72:75]
	v_mfma_f32_16x16x32_bf16 v[16:19], v[132:135], v[196:199], v[16:19]
	v_mfma_f32_16x16x32_bf16 v[12:15], v[156:159], v[196:199], v[12:15]
	v_mfma_f32_16x16x32_bf16 v[60:63], v[132:135], v[218:221], v[60:63]
	v_mfma_f32_16x16x32_bf16 v[68:71], v[156:159], v[218:221], v[68:71]
	v_mfma_f32_16x16x32_bf16 v[24:27], v[148:151], v[184:187], v[24:27]
	v_mfma_f32_16x16x32_bf16 v[20:23], v[160:163], v[184:187], v[20:23]
	v_mfma_f32_16x16x32_bf16 v[64:67], v[148:151], v[192:195], v[64:67]
	v_mfma_f32_16x16x32_bf16 v[72:75], v[160:163], v[192:195], v[72:75]
	v_mfma_f32_16x16x32_bf16 v[16:19], v[148:151], v[214:217], v[16:19]
	v_mfma_f32_16x16x32_bf16 v[12:15], v[160:163], v[214:217], v[12:15]
	v_mfma_f32_16x16x32_bf16 v[60:63], v[148:151], v[222:225], v[60:63]
	v_mfma_f32_16x16x32_bf16 v[68:71], v[160:163], v[222:225], v[68:71]


; #define PG8_MMA(ai, bj, At, Bt) do { __builtin_amdgcn_s_setprio(1); _Pragma("unroll") for (int m = 0; m < 4; ++m) _Pragma("unroll") for (int n = 0; n < 2; ++n) _Pragma("unroll") for (int k = 0; k < 2; ++k) \
;         acc[ai][bj][m][n] = __builtin_amdgcn_mfma_f32_16x16x32_bf16(Bt[n][k], At[m][k], acc[ai][bj][m][n], 0, 0, 0); __builtin_amdgcn_s_setprio(0); } while (0)
; #define PG8_WAIT_V(n) asm volatile("s_waitcnt vmcnt(" #n ")" ::: "memory")
; #define PG8_WAIT_L(n) asm volatile("s_waitcnt lgkmcnt(" #n ")" ::: "memory")
; #define PG8_BAR __builtin_amdgcn_s_barrier()
; #define PG8_SCHED __builtin_amdgcn_sched_barrier(0)
; template <class Epi, bool ALIGN_EPI>
; __device__ __forceinline__ void gemm_phase(LAS unsigned char* lds, const Gemm g, const StaticOrder& S, const Epi& E, const int tid) {
;     ...
;             PG8_WAIT_V(8); PG8_WAIT_L(0); PG8_BAR; PG8_MMA(1, 0, At, B0); PG8_MMA(1, 1, At, B1); PG8_BAR; PG8_SCHED;
	v_mfma_f32_16x16x32_bf16 v[128:131], v[164:167], v[180:183], v[128:131]
	v_mfma_f32_16x16x32_bf16 v[124:127], v[172:175], v[180:183], v[124:127]
	v_mfma_f32_16x16x32_bf16 v[120:123], v[164:167], v[188:191], v[120:123]
	v_mfma_f32_16x16x32_bf16 v[116:119], v[172:175], v[188:191], v[116:119]
	v_mfma_f32_16x16x32_bf16 v[112:115], v[164:167], v[196:199], v[112:115]
	v_mfma_f32_16x16x32_bf16 v[108:111], v[172:175], v[196:199], v[108:111]
	v_mfma_f32_16x16x32_bf16 v[104:107], v[164:167], v[218:221], v[104:107]
	v_mfma_f32_16x16x32_bf16 v[100:103], v[172:175], v[218:221], v[100:103]
	v_mfma_f32_16x16x32_bf16 v[128:131], v[168:171], v[184:187], v[128:131]
	v_mfma_f32_16x16x32_bf16 v[124:127], v[176:179], v[184:187], v[124:127]
	v_mfma_f32_16x16x32_bf16 v[120:123], v[168:171], v[192:195], v[120:123]
	v_mfma_f32_16x16x32_bf16 v[116:119], v[176:179], v[192:195], v[116:119]
	v_mfma_f32_16x16x32_bf16 v[112:115], v[168:171], v[214:217], v[112:115]
	v_mfma_f32_16x16x32_bf16 v[108:111], v[176:179], v[214:217], v[108:111]
	v_mfma_f32_16x16x32_bf16 v[104:107], v[168:171], v[222:225], v[104:107]
	v_mfma_f32_16x16x32_bf16 v[100:103], v[176:179], v[222:225], v[100:103]

; #define LAS __attribute__((address_space(3)))
; __device__ __forceinline__ unsigned cvt_pk_bf16(float lo, float hi) { unsigned r; asm volatile("v_cvt_pk_bf16_f32 %0, %1, %2" : "=v"(r) : "v"(lo), "v"(hi)); return r; }
; #define PG8_WAIT_V(n) asm volatile("s_waitcnt vmcnt(" #n ")" ::: "memory")
; #define PG8_WAIT_L(n) asm volatile("s_waitcnt lgkmcnt(" #n ")" ::: "memory")
; #define PG8_BAR __builtin_amdgcn_s_barrier()
; #define PG8_SCHED __builtin_amdgcn_sched_barrier(0)
; template <class Epi, bool ALIGN_EPI>
; __device__ __forceinline__ void gemm_phase(LAS unsigned char* lds, const Gemm g, const StaticOrder& S, const Epi& E, const int tid) {
;     ...
;             PG8_WAIT_V(8); PG8_WAIT_L(0); PG8_BAR; PG8_MMA(1, 0, At, B0); PG8_MMA(1, 1, At, B1); PG8_BAR; PG8_SCHED;
;         }
;         if constexpr (ALIGN_EPI) { if (wr == 0) PG8_BAR; }
;     __device__ __forceinline__ void operator()(f32x4 (&acc)[2][2][4][2], const Unit& u, int wr, int wc, LAS unsigned char* lds, int& rs_pm) const {
;         int fr, fq; epi_lane(fr, fq);
;         const int row0 = u.pm * BM + wr * 64 + fr, col0 = u.pn * BM + wc * 32 + 8 * fq; u32x4 zb = zero_frag();
; #pragma unroll
;         for (int ai = 0; ai < 2; ++ai)
; #pragma unroll
;             for (int m = 0; m < 4; ++m) { float ss = 0.f;
;                 bf16* const xrow = xb + (((size_t)(u.pm * 32 + u.pn * 4 + (wc >> 1)) * BM + (wr * 64 + fr + ai * HALF + m * 16)) * 64 + (wc & 1) * 32 + 8 * fq);
; #pragma unroll
;                 for (int bj = 0; bj < 2; ++bj) {
;                     const u32x4 xw = *(const u32x4*)(xrow + (size_t)bj * (2 * BM * 64));
;                     const f32x4 x0 = (f32x4){bflo(xw.x), bfhi(xw.x), bflo(xw.y), bfhi(xw.y)}, x1 = (f32x4){bflo(xw.z), bfhi(xw.z), bflo(xw.w), bfhi(xw.w)};
;                     const f32x4 v0 = x0 + acc[ai][bj][m][0] * alpha, v1 = x1 + acc[ai][bj][m][1] * alpha; zero_acc(acc[ai][bj][m][0], zb); zero_acc(acc[ai][bj][m][1], zb);
;                     ss += (v0[0] * v0[0] + v0[1] * v0[1]) + (v0[2] * v0[2] + v0[3] * v0[3]) + (v1[0] * v1[0] + v1[1] * v1[1]) + (v1[2] * v1[2] + v1[3] * v1[3]);
;                     u32x4 w; w.x = cvt_pk_bf16(v0[0], v0[1]); w.y = cvt_pk_bf16(v0[2], v0[3]); w.z = cvt_pk_bf16(v1[0], v1[1]); w.w = cvt_pk_bf16(v1[2], v1[3]);
;                     *(u32x4*)(xrow + (size_t)bj * (2 * BM * 64)) = w; }
	s_barrier
	s_add_i32 s86, s86, 2
	s_add_u32 s10, s10, 0x100
	s_addc_u32 s11, s11, 0
	s_add_u32 s84, s84, 0x10000
	s_addc_u32 s85, s85, 0
	s_cmp_gt_u32 s86, 29
	s_cbranch_scc0 .LBB0_847
	v_and_b32_e32 v222, 15, v238
	v_lshrrev_b32_e32 v156, 4, v238
	s_lshl_b32 s100, s40, 5
	s_lshl_b32 s101, s41, 2
	v_lshlrev_b32_e32 v222, 7, v222
	s_add_i32 s100, s100, s101
	s_or_b32 s100, s100, s80
	v_lshl_or_b32 v222, v156, 4, v222
	s_ashr_i32 s101, s100, 31
	s_lshl_b64 s[100:101], s[100:101], 15
	s_add_u32 s98, s74, s100
	s_addc_u32 s99, s75, s101
	s_add_u32 s98, s98, s30
	s_addc_u32 s99, s99, s31
	s_lshl_b32 s100, s77, 7
	s_add_u32 s98, s98, s100
	s_addc_u32 s99, s99, 0
	s_lshl_b32 s100, s40, 15
	s_lshl_b32 s101, s77, 7
	s_add_i32 s100, s100, s101
	s_lshl_b32 s101, s41, 4
	s_add_i32 s100, s100, s101
	s_lshl_b32 s101, s76, 2
	s_add_i32 s100, s100, s101
	s_add_u32 s22, s42, s100
	s_addc_u32 s23, s43, 0
	global_load_dwordx4 v[176:179], v222, s[98:99]
	s_add_u32 s100, s98, 0x10000
	s_addc_u32 s101, s99, 0
	global_load_dwordx4 v[180:183], v222, s[100:101]
	global_load_dwordx4 v[184:187], v222, s[98:99] offset:2048
	s_add_u32 s100, s98, 0x10000
	s_addc_u32 s101, s99, 0
	global_load_dwordx4 v[188:191], v222, s[100:101] offset:2048
	s_add_u32 s100, s98, 0x1000
	s_addc_u32 s101, s99, 0
	global_load_dwordx4 v[192:195], v222, s[100:101]
	s_add_u32 s100, s98, 0x11000
	s_addc_u32 s101, s99, 0
	global_load_dwordx4 v[196:199], v222, s[100:101]
	s_add_u32 s100, s98, 0x1000
	s_addc_u32 s101, s99, 0
	global_load_dwordx4 v[214:217], v222, s[100:101] offset:2048
	s_add_u32 s100, s98, 0x11000
	s_addc_u32 s101, s99, 0
	global_load_dwordx4 v[218:221], v222, s[100:101] offset:2048
	s_and_b64 vcc, exec, s[44:45]
	s_cbranch_vccz .LBB0_850
	s_barrier
.LBB0_850:
	v_mov_b32_e32 v132, v1
	v_mov_b32_e32 v133, v1
	v_mov_b32_e32 v134, v1
	v_mov_b32_e32 v135, v1
	v_xor_b32_e32 v174, 16, v238
	v_xor_b32_e32 v175, 32, v238
	v_lshlrev_b32_e32 v174, 2, v174
	v_lshlrev_b32_e32 v175, 2, v175
	s_waitcnt vmcnt(7)
	v_lshlrev_b32_e32 v156, 16, v176
	v_and_b32_e32 v157, 0xffff0000, v176
	v_lshlrev_b32_e32 v158, 16, v177
	v_and_b32_e32 v159, 0xffff0000, v177
	v_lshlrev_b32_e32 v160, 16, v178
	v_and_b32_e32 v161, 0xffff0000, v178
	v_lshlrev_b32_e32 v162, 16, v179
	v_and_b32_e32 v163, 0xffff0000, v179
	v_pk_add_f32 v[156:157], v[8:9], v[156:157]
	v_pk_add_f32 v[158:159], v[10:11], v[158:159]
	v_pk_add_f32 v[160:161], v[56:57], v[160:161]
	v_pk_add_f32 v[162:163], v[58:59], v[162:163]
	v_pk_mul_f32 v[164:165], v[156:157], v[156:157]
	v_pk_fma_f32 v[164:165], v[158:159], v[158:159], v[164:165]
	v_pk_fma_f32 v[164:165], v[160:161], v[160:161], v[164:165]
	v_pk_fma_f32 v[164:165], v[162:163], v[162:163], v[164:165]
	v_mfma_f32_16x16x32_bf16 v[8:11], v[132:135], v[132:135], 0
	v_mfma_f32_16x16x32_bf16 v[56:59], v[132:135], v[132:135], 0
	v_cvt_pk_bf16_f32 v176, v156, v157
	v_cvt_pk_bf16_f32 v177, v158, v159
	v_cvt_pk_bf16_f32 v178, v160, v161
	v_cvt_pk_bf16_f32 v179, v162, v163
	global_store_dwordx4 v222, v[176:179], s[98:99]
	s_nop 0
	s_add_u32 s100, s98, 0x4000
	s_addc_u32 s101, s99, 0
	global_load_dwordx4 v[176:179], v222, s[100:101]
	s_waitcnt vmcnt(8)
	v_lshlrev_b32_e32 v156, 16, v180
	v_and_b32_e32 v157, 0xffff0000, v180
	v_lshlrev_b32_e32 v158, 16, v181
	v_and_b32_e32 v159, 0xffff0000, v181
	v_lshlrev_b32_e32 v160, 16, v182
	v_and_b32_e32 v161, 0xffff0000, v182
	v_lshlrev_b32_e32 v162, 16, v183
	v_and_b32_e32 v163, 0xffff0000, v183
	v_pk_add_f32 v[156:157], v[4:5], v[156:157]
	v_pk_add_f32 v[158:159], v[6:7], v[158:159]
	v_pk_add_f32 v[160:161], v[28:29], v[160:161]
	v_pk_add_f32 v[162:163], v[30:31], v[162:163]
	v_pk_fma_f32 v[164:165], v[156:157], v[156:157], v[164:165]
	v_pk_fma_f32 v[164:165], v[158:159], v[158:159], v[164:165]
	v_pk_fma_f32 v[164:165], v[160:161], v[160:161], v[164:165]
	v_pk_fma_f32 v[164:165], v[162:163], v[162:163], v[164:165]
	v_mfma_f32_16x16x32_bf16 v[4:7], v[132:135], v[132:135], 0
	v_mfma_f32_16x16x32_bf16 v[28:31], v[132:135], v[132:135], 0
	v_cvt_pk_bf16_f32 v180, v156, v157
	v_cvt_pk_bf16_f32 v181, v158, v159
	v_cvt_pk_bf16_f32 v182, v160, v161
	v_cvt_pk_bf16_f32 v183, v162, v163
	s_add_u32 s100, s98, 0x10000
	s_addc_u32 s101, s99, 0
	global_store_dwordx4 v222, v[180:183], s[100:101]
	v_add_f32_e32 v166, v164, v165
	s_add_u32 s100, s98, 0x14000
	s_addc_u32 s101, s99, 0
	global_load_dwordx4 v[180:183], v222, s[100:101]
	s_waitcnt vmcnt(9)
	v_lshlrev_b32_e32 v156, 16, v184
	v_and_b32_e32 v157, 0xffff0000, v184
	v_lshlrev_b32_e32 v158, 16, v185
	v_and_b32_e32 v159, 0xffff0000, v185
	v_lshlrev_b32_e32 v160, 16, v186
	v_and_b32_e32 v161, 0xffff0000, v186
	v_lshlrev_b32_e32 v162, 16, v187
	v_and_b32_e32 v163, 0xffff0000, v187
	v_pk_add_f32 v[156:157], v[52:53], v[156:157]
	v_pk_add_f32 v[158:159], v[54:55], v[158:159]
	v_pk_add_f32 v[160:161], v[48:49], v[160:161]
	v_pk_add_f32 v[162:163], v[50:51], v[162:163]
	v_pk_mul_f32 v[164:165], v[156:157], v[156:157]
	v_pk_fma_f32 v[164:165], v[158:159], v[158:159], v[164:165]
	v_pk_fma_f32 v[164:165], v[160:161], v[160:161], v[164:165]
	v_pk_fma_f32 v[164:165], v[162:163], v[162:163], v[164:165]
	v_mfma_f32_16x16x32_bf16 v[52:55], v[132:135], v[132:135], 0
	v_mfma_f32_16x16x32_bf16 v[48:51], v[132:135], v[132:135], 0
	v_cvt_pk_bf16_f32 v184, v156, v157
	v_cvt_pk_bf16_f32 v185, v158, v159
	v_cvt_pk_bf16_f32 v186, v160, v161
	v_cvt_pk_bf16_f32 v187, v162, v163
	global_store_dwordx4 v222, v[184:187], s[98:99] offset:2048
	s_nop 0
	s_add_u32 s100, s98, 0x4000
	s_addc_u32 s101, s99, 0
	global_load_dwordx4 v[184:187], v222, s[100:101] offset:2048
	s_waitcnt vmcnt(10)
; __device__ __forceinline__ unsigned cvt_pk_bf16(float lo, float hi) { unsigned r; asm volatile("v_cvt_pk_bf16_f32 %0, %1, %2" : "=v"(r) : "v"(lo), "v"(hi)); return r; }
;     __device__ __forceinline__ void operator()(f32x4 (&acc)[2][2][4][2], const Unit& u, int wr, int wc, LAS unsigned char* lds, int& rs_pm) const {
;     ...
;             for (int m = 0; m < 4; ++m) { float ss = 0.f;
;                 bf16* const xrow = xb + (((size_t)(u.pm * 32 + u.pn * 4 + (wc >> 1)) * BM + (wr * 64 + fr + ai * HALF + m * 16)) * 64 + (wc & 1) * 32 + 8 * fq);
; #pragma unroll
;                 for (int bj = 0; bj < 2; ++bj) {
;                     const u32x4 xw = *(const u32x4*)(xrow + (size_t)bj * (2 * BM * 64));
;                     const f32x4 x0 = (f32x4){bflo(xw.x), bfhi(xw.x), bflo(xw.y), bfhi(xw.y)}, x1 = (f32x4){bflo(xw.z), bfhi(xw.z), bflo(xw.w), bfhi(xw.w)};
;                     const f32x4 v0 = x0 + acc[ai][bj][m][0] * alpha, v1 = x1 + acc[ai][bj][m][1] * alpha; zero_acc(acc[ai][bj][m][0], zb); zero_acc(acc[ai][bj][m][1], zb);
;                     ss += (v0[0] * v0[0] + v0[1] * v0[1]) + (v0[2] * v0[2] + v0[3] * v0[3]) + (v1[0] * v1[0] + v1[1] * v1[1]) + (v1[2] * v1[2] + v1[3] * v1[3]);
;                     u32x4 w; w.x = cvt_pk_bf16(v0[0], v0[1]); w.y = cvt_pk_bf16(v0[2], v0[3]); w.z = cvt_pk_bf16(v1[0], v1[1]); w.w = cvt_pk_bf16(v1[2], v1[3]);
;                     *(u32x4*)(xrow + (size_t)bj * (2 * BM * 64)) = w; }
	v_lshlrev_b32_e32 v156, 16, v188
	v_and_b32_e32 v157, 0xffff0000, v188
	v_lshlrev_b32_e32 v158, 16, v189
	v_and_b32_e32 v159, 0xffff0000, v189
	v_lshlrev_b32_e32 v160, 16, v190
	v_and_b32_e32 v161, 0xffff0000, v190
	v_lshlrev_b32_e32 v162, 16, v191
	v_and_b32_e32 v163, 0xffff0000, v191
	v_pk_add_f32 v[156:157], v[96:97], v[156:157]
	v_pk_add_f32 v[158:159], v[98:99], v[158:159]
	v_pk_add_f32 v[160:161], v[92:93], v[160:161]
	v_pk_add_f32 v[162:163], v[94:95], v[162:163]
	v_pk_fma_f32 v[164:165], v[156:157], v[156:157], v[164:165]
	v_pk_fma_f32 v[164:165], v[158:159], v[158:159], v[164:165]
	v_pk_fma_f32 v[164:165], v[160:161], v[160:161], v[164:165]
	v_pk_fma_f32 v[164:165], v[162:163], v[162:163], v[164:165]
	v_mfma_f32_16x16x32_bf16 v[96:99], v[132:135], v[132:135], 0
	v_mfma_f32_16x16x32_bf16 v[92:95], v[132:135], v[132:135], 0
	v_cvt_pk_bf16_f32 v188, v156, v157
	v_cvt_pk_bf16_f32 v189, v158, v159
	v_cvt_pk_bf16_f32 v190, v160, v161
	v_cvt_pk_bf16_f32 v191, v162, v163
	s_add_u32 s100, s98, 0x10000
	s_addc_u32 s101, s99, 0
	global_store_dwordx4 v222, v[188:191], s[100:101] offset:2048
	v_add_f32_e32 v167, v164, v165
	s_add_u32 s100, s98, 0x14000
	s_addc_u32 s101, s99, 0
	global_load_dwordx4 v[188:191], v222, s[100:101] offset:2048
	s_waitcnt vmcnt(11)
	v_lshlrev_b32_e32 v156, 16, v192
	v_and_b32_e32 v157, 0xffff0000, v192
	v_lshlrev_b32_e32 v158, 16, v193
	v_and_b32_e32 v159, 0xffff0000, v193
	v_lshlrev_b32_e32 v160, 16, v194
	v_and_b32_e32 v161, 0xffff0000, v194
	v_lshlrev_b32_e32 v162, 16, v195
	v_and_b32_e32 v163, 0xffff0000, v195
	v_pk_add_f32 v[156:157], v[44:45], v[156:157]
	v_pk_add_f32 v[158:159], v[46:47], v[158:159]
	v_pk_add_f32 v[160:161], v[40:41], v[160:161]
	v_pk_add_f32 v[162:163], v[42:43], v[162:163]
	v_pk_mul_f32 v[164:165], v[156:157], v[156:157]
	v_pk_fma_f32 v[164:165], v[158:159], v[158:159], v[164:165]
	v_pk_fma_f32 v[164:165], v[160:161], v[160:161], v[164:165]
	v_pk_fma_f32 v[164:165], v[162:163], v[162:163], v[164:165]
	v_mfma_f32_16x16x32_bf16 v[44:47], v[132:135], v[132:135], 0
	v_mfma_f32_16x16x32_bf16 v[40:43], v[132:135], v[132:135], 0
	v_cvt_pk_bf16_f32 v192, v156, v157
	v_cvt_pk_bf16_f32 v193, v158, v159
	v_cvt_pk_bf16_f32 v194, v160, v161
	v_cvt_pk_bf16_f32 v195, v162, v163
	s_add_u32 s100, s98, 0x1000
	s_addc_u32 s101, s99, 0
	global_store_dwordx4 v222, v[192:195], s[100:101]
	s_nop 0
	s_add_u32 s100, s98, 0x5000
	s_addc_u32 s101, s99, 0
	global_load_dwordx4 v[192:195], v222, s[100:101]
	s_waitcnt vmcnt(12)
	v_lshlrev_b32_e32 v156, 16, v196
	v_and_b32_e32 v157, 0xffff0000, v196
	v_lshlrev_b32_e32 v158, 16, v197
	v_and_b32_e32 v159, 0xffff0000, v197
	v_lshlrev_b32_e32 v160, 16, v198
	v_and_b32_e32 v161, 0xffff0000, v198
	v_lshlrev_b32_e32 v162, 16, v199
	v_and_b32_e32 v163, 0xffff0000, v199
	v_pk_add_f32 v[156:157], v[88:89], v[156:157]
	v_pk_add_f32 v[158:159], v[90:91], v[158:159]
	v_pk_add_f32 v[160:161], v[84:85], v[160:161]
	v_pk_add_f32 v[162:163], v[86:87], v[162:163]
	v_pk_fma_f32 v[164:165], v[156:157], v[156:157], v[164:165]
	v_pk_fma_f32 v[164:165], v[158:159], v[158:159], v[164:165]
	v_pk_fma_f32 v[164:165], v[160:161], v[160:161], v[164:165]
	v_pk_fma_f32 v[164:165], v[162:163], v[162:163], v[164:165]
	v_mfma_f32_16x16x32_bf16 v[88:91], v[132:135], v[132:135], 0
	v_mfma_f32_16x16x32_bf16 v[84:87], v[132:135], v[132:135], 0
	v_cvt_pk_bf16_f32 v196, v156, v157
	v_cvt_pk_bf16_f32 v197, v158, v159
	v_cvt_pk_bf16_f32 v198, v160, v161
	v_cvt_pk_bf16_f32 v199, v162, v163
	s_add_u32 s100, s98, 0x11000
	s_addc_u32 s101, s99, 0
	global_store_dwordx4 v222, v[196:199], s[100:101]
	v_add_f32_e32 v168, v164, v165
	s_add_u32 s100, s98, 0x15000
	s_addc_u32 s101, s99, 0
	global_load_dwordx4 v[196:199], v222, s[100:101]
	s_waitcnt vmcnt(13)
	v_lshlrev_b32_e32 v156, 16, v214
	v_and_b32_e32 v157, 0xffff0000, v214
	v_lshlrev_b32_e32 v158, 16, v215
	v_and_b32_e32 v159, 0xffff0000, v215
	v_lshlrev_b32_e32 v160, 16, v216
	v_and_b32_e32 v161, 0xffff0000, v216
	v_lshlrev_b32_e32 v162, 16, v217
	v_and_b32_e32 v163, 0xffff0000, v217
	v_pk_add_f32 v[156:157], v[36:37], v[156:157]
	v_pk_add_f32 v[158:159], v[38:39], v[158:159]
	v_pk_add_f32 v[160:161], v[32:33], v[160:161]
	v_pk_add_f32 v[162:163], v[34:35], v[162:163]
	v_pk_mul_f32 v[164:165], v[156:157], v[156:157]
	v_pk_fma_f32 v[164:165], v[158:159], v[158:159], v[164:165]
	v_pk_fma_f32 v[164:165], v[160:161], v[160:161], v[164:165]
	v_pk_fma_f32 v[164:165], v[162:163], v[162:163], v[164:165]
	v_mfma_f32_16x16x32_bf16 v[36:39], v[132:135], v[132:135], 0
	v_mfma_f32_16x16x32_bf16 v[32:35], v[132:135], v[132:135], 0
	v_cvt_pk_bf16_f32 v214, v156, v157
	v_cvt_pk_bf16_f32 v215, v158, v159
	v_cvt_pk_bf16_f32 v216, v160, v161
	v_cvt_pk_bf16_f32 v217, v162, v163
	s_add_u32 s100, s98, 0x1000
	s_addc_u32 s101, s99, 0
	global_store_dwordx4 v222, v[214:217], s[100:101] offset:2048
	s_nop 0
	s_add_u32 s100, s98, 0x5000
	s_addc_u32 s101, s99, 0
	global_load_dwordx4 v[214:217], v222, s[100:101] offset:2048
	s_waitcnt vmcnt(14)
	v_lshlrev_b32_e32 v156, 16, v218
	v_and_b32_e32 v157, 0xffff0000, v218
	v_lshlrev_b32_e32 v158, 16, v219
	v_and_b32_e32 v159, 0xffff0000, v219
	v_lshlrev_b32_e32 v160, 16, v220
	v_and_b32_e32 v161, 0xffff0000, v220
	v_lshlrev_b32_e32 v162, 16, v221
	v_and_b32_e32 v163, 0xffff0000, v221
	v_pk_add_f32 v[156:157], v[80:81], v[156:157]
	v_pk_add_f32 v[158:159], v[82:83], v[158:159]
	v_pk_add_f32 v[160:161], v[76:77], v[160:161]
	v_pk_add_f32 v[162:163], v[78:79], v[162:163]
	v_pk_fma_f32 v[164:165], v[156:157], v[156:157], v[164:165]
	v_pk_fma_f32 v[164:165], v[158:159], v[158:159], v[164:165]
	v_pk_fma_f32 v[164:165], v[160:161], v[160:161], v[164:165]
	v_pk_fma_f32 v[164:165], v[162:163], v[162:163], v[164:165]
	v_mfma_f32_16x16x32_bf16 v[80:83], v[132:135], v[132:135], 0
	v_mfma_f32_16x16x32_bf16 v[76:79], v[132:135], v[132:135], 0
	v_cvt_pk_bf16_f32 v218, v156, v157
	v_cvt_pk_bf16_f32 v219, v158, v159
	v_cvt_pk_bf16_f32 v220, v160, v161
	v_cvt_pk_bf16_f32 v221, v162, v163
	s_add_u32 s100, s98, 0x11000
	s_addc_u32 s101, s99, 0
	global_store_dwordx4 v222, v[218:221], s[100:101] offset:2048
	v_add_f32_e32 v169, v164, v165
	s_add_u32 s100, s98, 0x15000
	s_addc_u32 s101, s99, 0
	global_load_dwordx4 v[218:221], v222, s[100:101] offset:2048
	s_waitcnt vmcnt(14)
; __device__ __forceinline__ unsigned cvt_pk_bf16(float lo, float hi) { unsigned r; asm volatile("v_cvt_pk_bf16_f32 %0, %1, %2" : "=v"(r) : "v"(lo), "v"(hi)); return r; }
;     __device__ __forceinline__ void operator()(f32x4 (&acc)[2][2][4][2], const Unit& u, int wr, int wc, LAS unsigned char* lds, int& rs_pm) const {
;     ...
;             for (int m = 0; m < 4; ++m) { float ss = 0.f;
;                 bf16* const xrow = xb + (((size_t)(u.pm * 32 + u.pn * 4 + (wc >> 1)) * BM + (wr * 64 + fr + ai * HALF + m * 16)) * 64 + (wc & 1) * 32 + 8 * fq);
; #pragma unroll
;                 for (int bj = 0; bj < 2; ++bj) {
;                     const u32x4 xw = *(const u32x4*)(xrow + (size_t)bj * (2 * BM * 64));
;                     const f32x4 x0 = (f32x4){bflo(xw.x), bfhi(xw.x), bflo(xw.y), bfhi(xw.y)}, x1 = (f32x4){bflo(xw.z), bfhi(xw.z), bflo(xw.w), bfhi(xw.w)};
;                     const f32x4 v0 = x0 + acc[ai][bj][m][0] * alpha, v1 = x1 + acc[ai][bj][m][1] * alpha; zero_acc(acc[ai][bj][m][0], zb); zero_acc(acc[ai][bj][m][1], zb);
;                     ss += (v0[0] * v0[0] + v0[1] * v0[1]) + (v0[2] * v0[2] + v0[3] * v0[3]) + (v1[0] * v1[0] + v1[1] * v1[1]) + (v1[2] * v1[2] + v1[3] * v1[3]);
;                     u32x4 w; w.x = cvt_pk_bf16(v0[0], v0[1]); w.y = cvt_pk_bf16(v0[2], v0[3]); w.z = cvt_pk_bf16(v1[0], v1[1]); w.w = cvt_pk_bf16(v1[2], v1[3]);
;                     *(u32x4*)(xrow + (size_t)bj * (2 * BM * 64)) = w; }
	v_lshlrev_b32_e32 v156, 16, v176
	v_and_b32_e32 v157, 0xffff0000, v176
	v_lshlrev_b32_e32 v158, 16, v177
	v_and_b32_e32 v159, 0xffff0000, v177
	v_lshlrev_b32_e32 v160, 16, v178
	v_and_b32_e32 v161, 0xffff0000, v178
	v_lshlrev_b32_e32 v162, 16, v179
	v_and_b32_e32 v163, 0xffff0000, v179
	v_pk_add_f32 v[156:157], v[24:25], v[156:157]
	v_pk_add_f32 v[158:159], v[26:27], v[158:159]
	v_pk_add_f32 v[160:161], v[20:21], v[160:161]
	v_pk_add_f32 v[162:163], v[22:23], v[162:163]
	v_pk_mul_f32 v[164:165], v[156:157], v[156:157]
	v_pk_fma_f32 v[164:165], v[158:159], v[158:159], v[164:165]
	v_pk_fma_f32 v[164:165], v[160:161], v[160:161], v[164:165]
	v_pk_fma_f32 v[164:165], v[162:163], v[162:163], v[164:165]
	v_mfma_f32_16x16x32_bf16 v[24:27], v[132:135], v[132:135], 0
	v_mfma_f32_16x16x32_bf16 v[20:23], v[132:135], v[132:135], 0
	v_cvt_pk_bf16_f32 v176, v156, v157
	v_cvt_pk_bf16_f32 v177, v158, v159
	v_cvt_pk_bf16_f32 v178, v160, v161
	v_cvt_pk_bf16_f32 v179, v162, v163
	s_add_u32 s100, s98, 0x4000
	s_addc_u32 s101, s99, 0
	global_store_dwordx4 v222, v[176:179], s[100:101]
	s_nop 0
	s_waitcnt vmcnt(13)
	v_lshlrev_b32_e32 v156, 16, v180
	v_and_b32_e32 v157, 0xffff0000, v180
	v_lshlrev_b32_e32 v158, 16, v181
	v_and_b32_e32 v159, 0xffff0000, v181
	v_lshlrev_b32_e32 v160, 16, v182
	v_and_b32_e32 v161, 0xffff0000, v182
	v_lshlrev_b32_e32 v162, 16, v183
	v_and_b32_e32 v163, 0xffff0000, v183
	v_pk_add_f32 v[156:157], v[128:129], v[156:157]
	v_pk_add_f32 v[158:159], v[130:131], v[158:159]
	v_pk_add_f32 v[160:161], v[124:125], v[160:161]
	v_pk_add_f32 v[162:163], v[126:127], v[162:163]
	v_pk_fma_f32 v[164:165], v[156:157], v[156:157], v[164:165]
	v_pk_fma_f32 v[164:165], v[158:159], v[158:159], v[164:165]
	v_pk_fma_f32 v[164:165], v[160:161], v[160:161], v[164:165]
	v_pk_fma_f32 v[164:165], v[162:163], v[162:163], v[164:165]
	v_mfma_f32_16x16x32_bf16 v[128:131], v[132:135], v[132:135], 0
	v_mfma_f32_16x16x32_bf16 v[124:127], v[132:135], v[132:135], 0
	v_cvt_pk_bf16_f32 v180, v156, v157
	v_cvt_pk_bf16_f32 v181, v158, v159
	v_cvt_pk_bf16_f32 v182, v160, v161
	v_cvt_pk_bf16_f32 v183, v162, v163
	s_add_u32 s100, s98, 0x14000
	s_addc_u32 s101, s99, 0
	global_store_dwordx4 v222, v[180:183], s[100:101]
	v_add_f32_e32 v170, v164, v165
	s_waitcnt vmcnt(12)
	v_lshlrev_b32_e32 v156, 16, v184
	v_and_b32_e32 v157, 0xffff0000, v184
	v_lshlrev_b32_e32 v158, 16, v185
	v_and_b32_e32 v159, 0xffff0000, v185
	v_lshlrev_b32_e32 v160, 16, v186
	v_and_b32_e32 v161, 0xffff0000, v186
	v_lshlrev_b32_e32 v162, 16, v187
	v_and_b32_e32 v163, 0xffff0000, v187
	v_pk_add_f32 v[156:157], v[64:65], v[156:157]
	v_pk_add_f32 v[158:159], v[66:67], v[158:159]
	v_pk_add_f32 v[160:161], v[72:73], v[160:161]
	v_pk_add_f32 v[162:163], v[74:75], v[162:163]
	v_pk_mul_f32 v[164:165], v[156:157], v[156:157]
	v_pk_fma_f32 v[164:165], v[158:159], v[158:159], v[164:165]
	v_pk_fma_f32 v[164:165], v[160:161], v[160:161], v[164:165]
	v_pk_fma_f32 v[164:165], v[162:163], v[162:163], v[164:165]
	v_mfma_f32_16x16x32_bf16 v[64:67], v[132:135], v[132:135], 0
	v_mfma_f32_16x16x32_bf16 v[72:75], v[132:135], v[132:135], 0
	v_cvt_pk_bf16_f32 v184, v156, v157
	v_cvt_pk_bf16_f32 v185, v158, v159
	v_cvt_pk_bf16_f32 v186, v160, v161
	v_cvt_pk_bf16_f32 v187, v162, v163
	s_add_u32 s100, s98, 0x4000
	s_addc_u32 s101, s99, 0
	global_store_dwordx4 v222, v[184:187], s[100:101] offset:2048
	s_nop 0
	s_waitcnt vmcnt(11)
	v_lshlrev_b32_e32 v156, 16, v188
	v_and_b32_e32 v157, 0xffff0000, v188
	v_lshlrev_b32_e32 v158, 16, v189
	v_and_b32_e32 v159, 0xffff0000, v189
	v_lshlrev_b32_e32 v160, 16, v190
	v_and_b32_e32 v161, 0xffff0000, v190
	v_lshlrev_b32_e32 v162, 16, v191
	v_and_b32_e32 v163, 0xffff0000, v191
	v_pk_add_f32 v[156:157], v[120:121], v[156:157]
	v_pk_add_f32 v[158:159], v[122:123], v[158:159]
	v_pk_add_f32 v[160:161], v[116:117], v[160:161]
	v_pk_add_f32 v[162:163], v[118:119], v[162:163]
	v_pk_fma_f32 v[164:165], v[156:157], v[156:157], v[164:165]
	v_pk_fma_f32 v[164:165], v[158:159], v[158:159], v[164:165]
	v_pk_fma_f32 v[164:165], v[160:161], v[160:161], v[164:165]
	v_pk_fma_f32 v[164:165], v[162:163], v[162:163], v[164:165]
	v_mfma_f32_16x16x32_bf16 v[120:123], v[132:135], v[132:135], 0
	v_mfma_f32_16x16x32_bf16 v[116:119], v[132:135], v[132:135], 0
	v_cvt_pk_bf16_f32 v188, v156, v157
	v_cvt_pk_bf16_f32 v189, v158, v159
	v_cvt_pk_bf16_f32 v190, v160, v161
	v_cvt_pk_bf16_f32 v191, v162, v163
	s_add_u32 s100, s98, 0x14000
	s_addc_u32 s101, s99, 0
	global_store_dwordx4 v222, v[188:191], s[100:101] offset:2048
	v_add_f32_e32 v171, v164, v165
	s_waitcnt vmcnt(10)
	v_lshlrev_b32_e32 v156, 16, v192
	v_and_b32_e32 v157, 0xffff0000, v192
	v_lshlrev_b32_e32 v158, 16, v193
	v_and_b32_e32 v159, 0xffff0000, v193
	v_lshlrev_b32_e32 v160, 16, v194
	v_and_b32_e32 v161, 0xffff0000, v194
	v_lshlrev_b32_e32 v162, 16, v195
	v_and_b32_e32 v163, 0xffff0000, v195
	v_pk_add_f32 v[156:157], v[16:17], v[156:157]
	v_pk_add_f32 v[158:159], v[18:19], v[158:159]
	v_pk_add_f32 v[160:161], v[12:13], v[160:161]
	v_pk_add_f32 v[162:163], v[14:15], v[162:163]
	v_pk_mul_f32 v[164:165], v[156:157], v[156:157]
	v_pk_fma_f32 v[164:165], v[158:159], v[158:159], v[164:165]
	v_pk_fma_f32 v[164:165], v[160:161], v[160:161], v[164:165]
	v_pk_fma_f32 v[164:165], v[162:163], v[162:163], v[164:165]
	v_mfma_f32_16x16x32_bf16 v[16:19], v[132:135], v[132:135], 0
	v_mfma_f32_16x16x32_bf16 v[12:15], v[132:135], v[132:135], 0
	v_cvt_pk_bf16_f32 v192, v156, v157
	v_cvt_pk_bf16_f32 v193, v158, v159
	v_cvt_pk_bf16_f32 v194, v160, v161
	v_cvt_pk_bf16_f32 v195, v162, v163
	s_add_u32 s100, s98, 0x5000
	s_addc_u32 s101, s99, 0
	global_store_dwordx4 v222, v[192:195], s[100:101]
	s_nop 0
	s_waitcnt vmcnt(9)
; __device__ __forceinline__ unsigned cvt_pk_bf16(float lo, float hi) { unsigned r; asm volatile("v_cvt_pk_bf16_f32 %0, %1, %2" : "=v"(r) : "v"(lo), "v"(hi)); return r; }
;     __device__ __forceinline__ void operator()(f32x4 (&acc)[2][2][4][2], const Unit& u, int wr, int wc, LAS unsigned char* lds, int& rs_pm) const {
;     ...
;             for (int m = 0; m < 4; ++m) { float ss = 0.f;
;                 bf16* const xrow = xb + (((size_t)(u.pm * 32 + u.pn * 4 + (wc >> 1)) * BM + (wr * 64 + fr + ai * HALF + m * 16)) * 64 + (wc & 1) * 32 + 8 * fq);
; #pragma unroll
;                 for (int bj = 0; bj < 2; ++bj) {
;                     const u32x4 xw = *(const u32x4*)(xrow + (size_t)bj * (2 * BM * 64));
;                     const f32x4 x0 = (f32x4){bflo(xw.x), bfhi(xw.x), bflo(xw.y), bfhi(xw.y)}, x1 = (f32x4){bflo(xw.z), bfhi(xw.z), bflo(xw.w), bfhi(xw.w)};
;                     const f32x4 v0 = x0 + acc[ai][bj][m][0] * alpha, v1 = x1 + acc[ai][bj][m][1] * alpha; zero_acc(acc[ai][bj][m][0], zb); zero_acc(acc[ai][bj][m][1], zb);
;                     ss += (v0[0] * v0[0] + v0[1] * v0[1]) + (v0[2] * v0[2] + v0[3] * v0[3]) + (v1[0] * v1[0] + v1[1] * v1[1]) + (v1[2] * v1[2] + v1[3] * v1[3]);
;                     u32x4 w; w.x = cvt_pk_bf16(v0[0], v0[1]); w.y = cvt_pk_bf16(v0[2], v0[3]); w.z = cvt_pk_bf16(v1[0], v1[1]); w.w = cvt_pk_bf16(v1[2], v1[3]);
;                     *(u32x4*)(xrow + (size_t)bj * (2 * BM * 64)) = w; }
;                 ss += __shfl_xor(ss, 16); ss += __shfl_xor(ss, 32);
;                 if (fq == 0) part[(size_t)(row0 + ai * HALF + m * 16) * 32 + u.pn * 4 + wc] = ss;
;                 asm volatile("" ::: "memory"); }
	v_lshlrev_b32_e32 v156, 16, v196
	v_and_b32_e32 v157, 0xffff0000, v196
	v_lshlrev_b32_e32 v158, 16, v197
	v_and_b32_e32 v159, 0xffff0000, v197
	v_lshlrev_b32_e32 v160, 16, v198
	v_and_b32_e32 v161, 0xffff0000, v198
	v_lshlrev_b32_e32 v162, 16, v199
	v_and_b32_e32 v163, 0xffff0000, v199
	v_pk_add_f32 v[156:157], v[112:113], v[156:157]
	v_pk_add_f32 v[158:159], v[114:115], v[158:159]
	v_pk_add_f32 v[160:161], v[108:109], v[160:161]
	v_pk_add_f32 v[162:163], v[110:111], v[162:163]
	v_pk_fma_f32 v[164:165], v[156:157], v[156:157], v[164:165]
	v_pk_fma_f32 v[164:165], v[158:159], v[158:159], v[164:165]
	v_pk_fma_f32 v[164:165], v[160:161], v[160:161], v[164:165]
	v_pk_fma_f32 v[164:165], v[162:163], v[162:163], v[164:165]
	v_mfma_f32_16x16x32_bf16 v[112:115], v[132:135], v[132:135], 0
	v_mfma_f32_16x16x32_bf16 v[108:111], v[132:135], v[132:135], 0
	v_cvt_pk_bf16_f32 v196, v156, v157
	v_cvt_pk_bf16_f32 v197, v158, v159
	v_cvt_pk_bf16_f32 v198, v160, v161
	v_cvt_pk_bf16_f32 v199, v162, v163
	s_add_u32 s100, s98, 0x15000
	s_addc_u32 s101, s99, 0
	global_store_dwordx4 v222, v[196:199], s[100:101]
	v_add_f32_e32 v172, v164, v165
	s_waitcnt vmcnt(8)
	v_lshlrev_b32_e32 v156, 16, v214
	v_and_b32_e32 v157, 0xffff0000, v214
	v_lshlrev_b32_e32 v158, 16, v215
	v_and_b32_e32 v159, 0xffff0000, v215
	v_lshlrev_b32_e32 v160, 16, v216
	v_and_b32_e32 v161, 0xffff0000, v216
	v_lshlrev_b32_e32 v162, 16, v217
	v_and_b32_e32 v163, 0xffff0000, v217
	v_pk_add_f32 v[156:157], v[60:61], v[156:157]
	v_pk_add_f32 v[158:159], v[62:63], v[158:159]
	v_pk_add_f32 v[160:161], v[68:69], v[160:161]
	v_pk_add_f32 v[162:163], v[70:71], v[162:163]
	v_pk_mul_f32 v[164:165], v[156:157], v[156:157]
	v_pk_fma_f32 v[164:165], v[158:159], v[158:159], v[164:165]
	v_pk_fma_f32 v[164:165], v[160:161], v[160:161], v[164:165]
	v_pk_fma_f32 v[164:165], v[162:163], v[162:163], v[164:165]
	v_mfma_f32_16x16x32_bf16 v[60:63], v[132:135], v[132:135], 0
	v_mfma_f32_16x16x32_bf16 v[68:71], v[132:135], v[132:135], 0
	v_cvt_pk_bf16_f32 v214, v156, v157
	v_cvt_pk_bf16_f32 v215, v158, v159
	v_cvt_pk_bf16_f32 v216, v160, v161
	v_cvt_pk_bf16_f32 v217, v162, v163
	s_add_u32 s100, s98, 0x5000
	s_addc_u32 s101, s99, 0
	global_store_dwordx4 v222, v[214:217], s[100:101] offset:2048
	s_nop 0
	s_waitcnt vmcnt(7)
	v_lshlrev_b32_e32 v156, 16, v218
	v_and_b32_e32 v157, 0xffff0000, v218
	v_lshlrev_b32_e32 v158, 16, v219
	v_and_b32_e32 v159, 0xffff0000, v219
	v_lshlrev_b32_e32 v160, 16, v220
	v_and_b32_e32 v161, 0xffff0000, v220
	v_lshlrev_b32_e32 v162, 16, v221
	v_and_b32_e32 v163, 0xffff0000, v221
	v_pk_add_f32 v[156:157], v[104:105], v[156:157]
	v_pk_add_f32 v[158:159], v[106:107], v[158:159]
	v_pk_add_f32 v[160:161], v[100:101], v[160:161]
	v_pk_add_f32 v[162:163], v[102:103], v[162:163]
	v_pk_fma_f32 v[164:165], v[156:157], v[156:157], v[164:165]
	v_pk_fma_f32 v[164:165], v[158:159], v[158:159], v[164:165]
	v_pk_fma_f32 v[164:165], v[160:161], v[160:161], v[164:165]
	v_pk_fma_f32 v[164:165], v[162:163], v[162:163], v[164:165]
	v_mfma_f32_16x16x32_bf16 v[104:107], v[132:135], v[132:135], 0
	v_mfma_f32_16x16x32_bf16 v[100:103], v[132:135], v[132:135], 0
	v_cvt_pk_bf16_f32 v218, v156, v157
	v_cvt_pk_bf16_f32 v219, v158, v159
	v_cvt_pk_bf16_f32 v220, v160, v161
	v_cvt_pk_bf16_f32 v221, v162, v163
	s_add_u32 s100, s98, 0x15000
	s_addc_u32 s101, s99, 0
	global_store_dwordx4 v222, v[218:221], s[100:101] offset:2048
	v_add_f32_e32 v173, v164, v165
	ds_bpermute_b32 v156, v174, v166
	ds_bpermute_b32 v157, v174, v167
	ds_bpermute_b32 v158, v174, v168
	ds_bpermute_b32 v159, v174, v169
	ds_bpermute_b32 v160, v174, v170
	ds_bpermute_b32 v161, v174, v171
	ds_bpermute_b32 v162, v174, v172
	ds_bpermute_b32 v163, v174, v173
	s_waitcnt lgkmcnt(0)
	v_add_f32_e32 v166, v166, v156
	v_add_f32_e32 v167, v167, v157
	v_add_f32_e32 v168, v168, v158
	v_add_f32_e32 v169, v169, v159
	v_add_f32_e32 v170, v170, v160
	v_add_f32_e32 v171, v171, v161
	v_add_f32_e32 v172, v172, v162
	v_add_f32_e32 v173, v173, v163
	ds_bpermute_b32 v156, v175, v166
	ds_bpermute_b32 v157, v175, v167
	ds_bpermute_b32 v158, v175, v168
	ds_bpermute_b32 v159, v175, v169
	ds_bpermute_b32 v160, v175, v170
	ds_bpermute_b32 v161, v175, v171
	ds_bpermute_b32 v162, v175, v172
	ds_bpermute_b32 v163, v175, v173
	s_waitcnt lgkmcnt(0)
	v_add_f32_e32 v166, v166, v156
	v_add_f32_e32 v167, v167, v157
	v_add_f32_e32 v168, v168, v158
	v_add_f32_e32 v169, v169, v159
	v_add_f32_e32 v170, v170, v160
	v_add_f32_e32 v171, v171, v161
	v_add_f32_e32 v172, v172, v162
	v_add_f32_e32 v173, v173, v163
	s_mov_b64 s[34:35], exec
	s_mov_b64 exec, 0xffff
	global_store_dword v222, v166, s[22:23]
	global_store_dword v222, v167, s[22:23] offset:2048
	s_add_u32 s100, s22, 0x1000
	s_addc_u32 s101, s23, 0
	global_store_dword v222, v168, s[100:101]
	s_add_u32 s100, s22, 0x1000
	s_addc_u32 s101, s23, 0
	global_store_dword v222, v169, s[100:101] offset:2048
	s_add_u32 s100, s22, 0x4000
	s_addc_u32 s101, s23, 0
	global_store_dword v222, v170, s[100:101]
	s_add_u32 s100, s22, 0x4000
	s_addc_u32 s101, s23, 0
	global_store_dword v222, v171, s[100:101] offset:2048
	s_add_u32 s100, s22, 0x5000
	s_addc_u32 s101, s23, 0
	global_store_dword v222, v172, s[100:101]
	s_add_u32 s100, s22, 0x5000
	s_addc_u32 s101, s23, 0
	global_store_dword v222, v173, s[100:101] offset:2048
	s_mov_b64 exec, s[34:35]
	s_andn2_b64 vcc, exec, s[38:39]
	s_mov_b64 s[10:11], -1
	s_cbranch_vccnz .LBB0_843
	s_andn2_b64 vcc, exec, s[18:19]
	s_cbranch_vccnz .LBB0_842
	s_barrier
	s_branch .LBB0_842
